# write-through (sc0 sc1) stores in all GEMM epilogues
# baseline (speedup 1.0000x reference)
.LBB0_352:
	v_lshl_or_b32 v148, s66, 8, v152
	v_lshl_add_u32 v157, s65, 8, v1
	v_mov_b64_e32 v[146:147], s[8:9]
	v_ashrrev_i32_e32 v149, 31, v148
	v_mad_i64_i32 v[162:163], s[30:31], v157, s53, v[146:147]
	v_lshlrev_b64 v[148:149], 1, v[148:149]
	v_cvt_pk_bf16_f32 v158, v126, v127
	v_cvt_pk_bf16_f32 v159, v128, v129
	v_cvt_pk_bf16_f32 v160, v122, v123
	v_cvt_pk_bf16_f32 v161, v124, v125
	v_lshl_add_u64 v[162:163], v[162:163], 0, v[148:149]
	global_store_dwordx4 v[162:163], v[158:161], off sc0 sc1
	s_nop 1
	v_cvt_pk_bf16_f32 v158, v114, v115
	v_cvt_pk_bf16_f32 v159, v116, v117
	v_cvt_pk_bf16_f32 v160, v106, v107
	v_cvt_pk_bf16_f32 v161, v108, v109
	global_store_dwordx4 v[162:163], v[158:161], off offset:256 sc0 sc1
	v_or_b32_e32 v162, 16, v157
	v_mad_i64_i32 v[162:163], s[30:31], v162, s53, v[146:147]
	v_cvt_pk_bf16_f32 v158, v118, v119
	v_cvt_pk_bf16_f32 v159, v120, v121
	v_cvt_pk_bf16_f32 v160, v110, v111
	v_cvt_pk_bf16_f32 v161, v112, v113
	v_lshl_add_u64 v[162:163], v[162:163], 0, v[148:149]
	global_store_dwordx4 v[162:163], v[158:161], off sc0 sc1
	s_nop 1
	v_cvt_pk_bf16_f32 v158, v98, v99
	v_cvt_pk_bf16_f32 v159, v100, v101
	v_cvt_pk_bf16_f32 v160, v90, v91
	v_cvt_pk_bf16_f32 v161, v92, v93
	global_store_dwordx4 v[162:163], v[158:161], off offset:256 sc0 sc1
	v_or_b32_e32 v162, 32, v157
	v_mad_i64_i32 v[162:163], s[30:31], v162, s53, v[146:147]
	v_cvt_pk_bf16_f32 v158, v102, v103
	v_cvt_pk_bf16_f32 v159, v104, v105
	v_cvt_pk_bf16_f32 v160, v94, v95
	v_cvt_pk_bf16_f32 v161, v96, v97
	v_lshl_add_u64 v[162:163], v[162:163], 0, v[148:149]
	global_store_dwordx4 v[162:163], v[158:161], off sc0 sc1
	s_nop 1
	v_cvt_pk_bf16_f32 v158, v82, v83
	v_cvt_pk_bf16_f32 v159, v84, v85
	v_cvt_pk_bf16_f32 v160, v74, v75
	v_cvt_pk_bf16_f32 v161, v76, v77
	global_store_dwordx4 v[162:163], v[158:161], off offset:256 sc0 sc1
	v_or_b32_e32 v162, 48, v157
	v_mad_i64_i32 v[162:163], s[30:31], v162, s53, v[146:147]
	v_cvt_pk_bf16_f32 v158, v86, v87
	v_cvt_pk_bf16_f32 v159, v88, v89
	v_cvt_pk_bf16_f32 v160, v78, v79
	v_cvt_pk_bf16_f32 v161, v80, v81
	v_lshl_add_u64 v[162:163], v[162:163], 0, v[148:149]
	global_store_dwordx4 v[162:163], v[158:161], off sc0 sc1
	s_nop 1
	v_cvt_pk_bf16_f32 v158, v70, v71
	v_cvt_pk_bf16_f32 v159, v72, v73
	v_cvt_pk_bf16_f32 v160, v66, v67
	v_cvt_pk_bf16_f32 v161, v68, v69
	global_store_dwordx4 v[162:163], v[158:161], off offset:256 sc0 sc1
	v_add_u32_e32 v162, 0x80, v157
	v_mad_i64_i32 v[162:163], s[30:31], v162, s53, v[146:147]
	v_cvt_pk_bf16_f32 v158, v62, v63
	v_cvt_pk_bf16_f32 v159, v64, v65
	v_cvt_pk_bf16_f32 v160, v58, v59
	v_cvt_pk_bf16_f32 v161, v60, v61
	v_lshl_add_u64 v[162:163], v[162:163], 0, v[148:149]
	global_store_dwordx4 v[162:163], v[158:161], off sc0 sc1
	s_nop 1
	v_cvt_pk_bf16_f32 v158, v50, v51
	v_cvt_pk_bf16_f32 v159, v52, v53
	v_cvt_pk_bf16_f32 v160, v42, v43
	v_cvt_pk_bf16_f32 v161, v44, v45
	global_store_dwordx4 v[162:163], v[158:161], off offset:256 sc0 sc1
	v_add_u32_e32 v162, 0x90, v157
	v_mad_i64_i32 v[162:163], s[30:31], v162, s53, v[146:147]
	v_cvt_pk_bf16_f32 v158, v54, v55
	v_cvt_pk_bf16_f32 v159, v56, v57
	v_cvt_pk_bf16_f32 v160, v46, v47
	v_cvt_pk_bf16_f32 v161, v48, v49
	v_lshl_add_u64 v[162:163], v[162:163], 0, v[148:149]
	global_store_dwordx4 v[162:163], v[158:161], off sc0 sc1
	s_nop 1
	v_cvt_pk_bf16_f32 v158, v34, v35
	v_cvt_pk_bf16_f32 v159, v36, v37
	v_cvt_pk_bf16_f32 v160, v26, v27
	v_cvt_pk_bf16_f32 v161, v28, v29
	global_store_dwordx4 v[162:163], v[158:161], off offset:256 sc0 sc1
	v_add_u32_e32 v162, 0xa0, v157
	v_mad_i64_i32 v[162:163], s[30:31], v162, s53, v[146:147]
	v_add_u32_e32 v157, 0xb0, v157
	v_cvt_pk_bf16_f32 v158, v38, v39
	v_cvt_pk_bf16_f32 v159, v40, v41
	v_cvt_pk_bf16_f32 v160, v30, v31
	v_cvt_pk_bf16_f32 v161, v32, v33
	v_lshl_add_u64 v[162:163], v[162:163], 0, v[148:149]
	v_mad_i64_i32 v[146:147], s[30:31], v157, s53, v[146:147]
	global_store_dwordx4 v[162:163], v[158:161], off sc0 sc1
	s_nop 1
	v_cvt_pk_bf16_f32 v158, v18, v19
	v_cvt_pk_bf16_f32 v159, v20, v21
	v_cvt_pk_bf16_f32 v160, v10, v11
	v_cvt_pk_bf16_f32 v161, v12, v13
	global_store_dwordx4 v[162:163], v[158:161], off offset:256 sc0 sc1
	v_lshl_add_u64 v[162:163], v[146:147], 0, v[148:149]
	v_cvt_pk_bf16_f32 v146, v6, v7
	v_cvt_pk_bf16_f32 v147, v8, v9
	v_cvt_pk_bf16_f32 v148, v2, v3
	v_cvt_pk_bf16_f32 v149, v4, v5
	s_nop 0
	v_cvt_pk_bf16_f32 v158, v22, v23
	v_cvt_pk_bf16_f32 v159, v24, v25
	v_cvt_pk_bf16_f32 v160, v14, v15
	v_cvt_pk_bf16_f32 v161, v16, v17
	global_store_dwordx4 v[162:163], v[158:161], off sc0 sc1
	global_store_dwordx4 v[162:163], v[146:149], off offset:256 sc0 sc1
	s_cbranch_execnz .LBB0_350
.LBB0_353:
	s_nop 0
	v_lshl_add_u32 v148, s66, 8, v151
	v_lshl_or_b32 v146, s65, 8, v152
	v_ashrrev_i32_e32 v149, 31, v148
	v_ashrrev_i32_e32 v147, 31, v146
	v_lshlrev_b64 v[158:159], 14, v[148:149]
	v_lshl_add_u64 v[158:159], s[10:11], 0, v[158:159]
	v_lshlrev_b64 v[160:161], 1, v[146:147]
	v_lshl_add_u64 v[146:147], v[158:159], 0, v[160:161]
	v_cvt_pk_bf16_f32 v62, v62, v63
	v_cvt_pk_bf16_f32 v63, v64, v65
	v_cvt_pk_bf16_f32 v64, v58, v59
	v_add_co_u32_e32 v58, vcc, s60, v146
	v_cvt_pk_bf16_f32 v114, v114, v115
	v_cvt_pk_bf16_f32 v115, v116, v117
	v_cvt_pk_bf16_f32 v116, v106, v107
	v_or_b32_e32 v106, 16, v148
	s_nop 0
	v_addc_co_u32_e32 v59, vcc, 0, v147, vcc
	v_ashrrev_i32_e32 v107, 31, v106
	v_cvt_pk_bf16_f32 v98, v98, v99
	v_cvt_pk_bf16_f32 v99, v100, v101
	v_cvt_pk_bf16_f32 v100, v90, v91
	v_or_b32_e32 v90, 32, v148
	v_cvt_pk_bf16_f32 v50, v50, v51
	v_cvt_pk_bf16_f32 v51, v52, v53
	v_cvt_pk_bf16_f32 v53, v44, v45
	v_cvt_pk_bf16_f32 v44, v46, v47
	v_add_co_u32_e32 v46, vcc, s61, v146
	v_lshlrev_b64 v[106:107], 14, v[106:107]
	v_ashrrev_i32_e32 v91, 31, v90
	v_cvt_pk_bf16_f32 v82, v82, v83
	v_cvt_pk_bf16_f32 v83, v84, v85
	v_cvt_pk_bf16_f32 v84, v74, v75
	v_or_b32_e32 v74, 48, v148
	v_addc_co_u32_e32 v47, vcc, 0, v147, vcc
	v_lshl_add_u64 v[106:107], s[10:11], 0, v[106:107]
	v_lshlrev_b64 v[90:91], 14, v[90:91]
	v_ashrrev_i32_e32 v75, 31, v74
	v_cvt_pk_bf16_f32 v70, v70, v71
	v_cvt_pk_bf16_f32 v71, v72, v73
	v_cvt_pk_bf16_f32 v72, v66, v67
	v_lshl_add_u64 v[66:67], v[146:147], 0, s[16:17]
	v_cvt_pk_bf16_f32 v34, v34, v35
	v_cvt_pk_bf16_f32 v35, v36, v37
	v_cvt_pk_bf16_f32 v37, v28, v29
	v_cvt_pk_bf16_f32 v28, v30, v31
	v_add_co_u32_e32 v30, vcc, s62, v146
	v_cvt_pk_bf16_f32 v117, v108, v109
	global_store_dwordx4 v[146:147], v[114:117], off offset:256 sc0 sc1
	v_lshl_add_u64 v[90:91], s[10:11], 0, v[90:91]
	v_lshlrev_b64 v[74:75], 14, v[74:75]
	v_lshl_add_u64 v[114:115], v[106:107], 0, v[160:161]
	v_cvt_pk_bf16_f32 v52, v42, v43
	global_store_dwordx4 v[66:67], v[50:53], off offset:256 sc0 sc1
	v_addc_co_u32_e32 v31, vcc, 0, v147, vcc
	s_nop 0
	v_lshl_add_u64 v[50:51], v[146:147], 0, s[18:19]
	v_cvt_pk_bf16_f32 v101, v92, v93
	global_store_dwordx4 v[114:115], v[98:101], off offset:256 sc0 sc1
	v_lshl_add_u64 v[74:75], s[10:11], 0, v[74:75]
	v_cvt_pk_bf16_f32 v36, v26, v27
	global_store_dwordx4 v[50:51], v[34:37], off offset:256 sc0 sc1
	v_lshl_add_u64 v[98:99], v[90:91], 0, v[160:161]
	v_cvt_pk_bf16_f32 v18, v18, v19
	v_cvt_pk_bf16_f32 v19, v20, v21
	v_cvt_pk_bf16_f32 v21, v12, v13
	v_cvt_pk_bf16_f32 v12, v14, v15
	s_nop 0
	v_lshl_add_u64 v[34:35], v[146:147], 0, s[20:21]
	v_add_co_u32_e32 v14, vcc, s63, v146
	v_cvt_pk_bf16_f32 v85, v76, v77
	global_store_dwordx4 v[98:99], v[82:85], off offset:256 sc0 sc1
	v_cvt_pk_bf16_f32 v20, v10, v11
	global_store_dwordx4 v[34:35], v[18:21], off offset:256 sc0 sc1
	v_addc_co_u32_e32 v15, vcc, 0, v147, vcc
	v_lshl_add_u64 v[82:83], v[74:75], 0, v[160:161]
	v_lshl_add_u64 v[18:19], v[146:147], 0, s[22:23]
	v_cvt_pk_bf16_f32 v126, v126, v127
	v_cvt_pk_bf16_f32 v127, v128, v129
	v_cvt_pk_bf16_f32 v128, v122, v123
	v_cvt_pk_bf16_f32 v129, v124, v125
	global_store_dwordx4 v[146:147], v[126:129], off sc0 sc1
	v_cvt_pk_bf16_f32 v106, v118, v119
	v_cvt_pk_bf16_f32 v107, v120, v121
	v_cvt_pk_bf16_f32 v108, v110, v111
	v_cvt_pk_bf16_f32 v109, v112, v113
	global_store_dwordx4 v[114:115], v[106:109], off sc0 sc1
	v_cvt_pk_bf16_f32 v90, v102, v103
	v_cvt_pk_bf16_f32 v91, v104, v105
	v_cvt_pk_bf16_f32 v92, v94, v95
	v_cvt_pk_bf16_f32 v93, v96, v97
	global_store_dwordx4 v[98:99], v[90:93], off sc0 sc1
	v_cvt_pk_bf16_f32 v74, v86, v87
	v_cvt_pk_bf16_f32 v75, v88, v89
	v_cvt_pk_bf16_f32 v76, v78, v79
	v_cvt_pk_bf16_f32 v77, v80, v81
	global_store_dwordx4 v[82:83], v[74:77], off sc0 sc1
	v_cvt_pk_bf16_f32 v73, v68, v69
	global_store_dwordx4 v[82:83], v[70:73], off offset:256 sc0 sc1
	v_cvt_pk_bf16_f32 v65, v60, v61
	global_store_dwordx4 v[58:59], v[62:65], off sc0 sc1
	v_cvt_pk_bf16_f32 v42, v54, v55
	v_cvt_pk_bf16_f32 v43, v56, v57
	v_cvt_pk_bf16_f32 v45, v48, v49
	global_store_dwordx4 v[46:47], v[42:45], off sc0 sc1
	v_cvt_pk_bf16_f32 v26, v38, v39
	v_cvt_pk_bf16_f32 v27, v40, v41
	v_cvt_pk_bf16_f32 v29, v32, v33
	global_store_dwordx4 v[30:31], v[26:29], off sc0 sc1
	v_cvt_pk_bf16_f32 v10, v22, v23
	v_cvt_pk_bf16_f32 v11, v24, v25
	v_cvt_pk_bf16_f32 v13, v16, v17
	global_store_dwordx4 v[14:15], v[10:13], off sc0 sc1
	v_cvt_pk_bf16_f32 v6, v6, v7
	v_cvt_pk_bf16_f32 v7, v8, v9
	v_cvt_pk_bf16_f32 v8, v2, v3
	v_cvt_pk_bf16_f32 v9, v4, v5
	global_store_dwordx4 v[18:19], v[6:9], off offset:256 sc0 sc1
	s_and_b64 vcc, exec, s[4:5]
	s_mov_b64 s[4:5], -1
	s_cbranch_vccnz .LBB0_332

.LBB0_894:
	v_lshl_or_b32 v146, s53, 8, v153
	v_lshl_add_u32 v148, s22, 8, v1
	v_mov_b64_e32 v[150:151], s[8:9]
	v_ashrrev_i32_e32 v147, 31, v146
	v_mad_i64_i32 v[158:159], s[24:25], v148, s45, v[150:151]
	v_lshlrev_b64 v[146:147], 1, v[146:147]
	v_lshl_add_u64 v[162:163], v[158:159], 0, v[146:147]
	global_load_dwordx4 v[158:161], v[162:163], off
	v_ashrrev_i32_e32 v149, 31, v148
	v_lshlrev_b64 v[164:165], 12, v[148:149]
	v_lshl_add_u64 v[164:165], s[6:7], 0, v[164:165]
	v_lshl_add_u64 v[170:171], v[164:165], 0, v[146:147]
	global_load_dwordx4 v[162:165], v[162:163], off offset:256
	v_or_b32_e32 v166, 16, v148
	v_mad_i64_i32 v[168:169], s[24:25], v166, s45, v[150:151]
	v_lshl_add_u64 v[168:169], v[168:169], 0, v[146:147]
	s_andn2_b64 vcc, exec, s[4:5]
	s_mov_b64 s[4:5], -1
	s_waitcnt vmcnt(0)
	v_lshlrev_b32_e32 v173, 16, v161
	v_and_b32_e32 v161, 0xffff0000, v161
	v_lshlrev_b32_e32 v149, 16, v158
	v_and_b32_e32 v158, 0xffff0000, v158
	v_lshlrev_b32_e32 v167, 16, v159
	v_and_b32_e32 v159, 0xffff0000, v159
	v_lshlrev_b32_e32 v172, 16, v160
	v_and_b32_e32 v160, 0xffff0000, v160
	v_mul_f32_e32 v161, 0xbfb8aa3b, v161
	v_mul_f32_e32 v149, 0xbfb8aa3b, v149
	v_mul_f32_e32 v158, 0xbfb8aa3b, v158
	v_mul_f32_e32 v167, 0xbfb8aa3b, v167
	v_mul_f32_e32 v159, 0xbfb8aa3b, v159
	v_mul_f32_e32 v172, 0xbfb8aa3b, v172
	v_mul_f32_e32 v160, 0xbfb8aa3b, v160
	v_mul_f32_e32 v173, 0xbfb8aa3b, v173
	v_exp_f32_e32 v161, v161
	v_exp_f32_e32 v149, v149
	v_exp_f32_e32 v158, v158
	v_exp_f32_e32 v167, v167
	v_exp_f32_e32 v159, v159
	v_exp_f32_e32 v172, v172
	v_exp_f32_e32 v160, v160
	v_exp_f32_e32 v173, v173
	v_add_f32_e32 v161, 1.0, v161
	v_add_f32_e32 v149, 1.0, v149
	v_add_f32_e32 v158, 1.0, v158
	v_add_f32_e32 v167, 1.0, v167
	v_add_f32_e32 v159, 1.0, v159
	v_add_f32_e32 v172, 1.0, v172
	v_add_f32_e32 v160, 1.0, v160
	v_add_f32_e32 v173, 1.0, v173
	v_rcp_f32_e32 v161, v161
	v_rcp_f32_e32 v149, v149
	v_rcp_f32_e32 v158, v158
	v_rcp_f32_e32 v167, v167
	v_rcp_f32_e32 v159, v159
	v_rcp_f32_e32 v172, v172
	v_rcp_f32_e32 v160, v160
	v_rcp_f32_e32 v173, v173
	v_mul_f32_e32 v125, v125, v161
	v_mul_f32_e32 v126, v126, v149
	v_mul_f32_e32 v127, v127, v158
	v_mul_f32_e32 v128, v128, v167
	v_mul_f32_e32 v129, v129, v159
	v_mul_f32_e32 v149, v122, v172
	v_mul_f32_e32 v158, v123, v160
	v_mul_f32_e32 v159, v124, v173
	v_cvt_pk_bf16_f32 v122, v126, v127
	v_cvt_pk_bf16_f32 v123, v128, v129
	v_cvt_pk_bf16_f32 v124, v149, v158
	v_cvt_pk_bf16_f32 v125, v159, v125
	global_store_dwordx4 v[170:171], v[122:125], off sc0 sc1
	global_load_dwordx4 v[124:127], v[168:169], off
	v_and_b32_e32 v149, 0xffff0000, v162
	v_lshlrev_b32_e32 v123, 16, v162
	v_lshlrev_b32_e32 v160, 16, v163
	v_and_b32_e32 v161, 0xffff0000, v163
	v_lshlrev_b32_e32 v162, 16, v164
	v_and_b32_e32 v163, 0xffff0000, v164
	v_lshlrev_b32_e32 v164, 16, v165
	v_and_b32_e32 v165, 0xffff0000, v165
	v_mul_f32_e32 v165, 0xbfb8aa3b, v165
	v_mul_f32_e32 v123, 0xbfb8aa3b, v123
	v_mul_f32_e32 v149, 0xbfb8aa3b, v149
	v_mul_f32_e32 v160, 0xbfb8aa3b, v160
	v_mul_f32_e32 v161, 0xbfb8aa3b, v161
	v_mul_f32_e32 v162, 0xbfb8aa3b, v162
	v_mul_f32_e32 v163, 0xbfb8aa3b, v163
	v_mul_f32_e32 v164, 0xbfb8aa3b, v164
	v_exp_f32_e32 v165, v165
	v_exp_f32_e32 v123, v123
	v_exp_f32_e32 v149, v149
	v_exp_f32_e32 v160, v160
	v_exp_f32_e32 v161, v161
	v_exp_f32_e32 v162, v162
	v_exp_f32_e32 v163, v163
	v_exp_f32_e32 v164, v164
	v_add_f32_e32 v165, 1.0, v165
	v_add_f32_e32 v123, 1.0, v123
	v_add_f32_e32 v149, 1.0, v149
	v_add_f32_e32 v160, 1.0, v160
	v_add_f32_e32 v161, 1.0, v161
	v_add_f32_e32 v162, 1.0, v162
	v_add_f32_e32 v163, 1.0, v163
	v_add_f32_e32 v164, 1.0, v164
	v_rcp_f32_e32 v165, v165
	v_rcp_f32_e32 v123, v123
	v_rcp_f32_e32 v149, v149
	v_rcp_f32_e32 v160, v160
	v_rcp_f32_e32 v161, v161
	v_rcp_f32_e32 v162, v162
	v_rcp_f32_e32 v163, v163
	v_rcp_f32_e32 v164, v164
	v_mul_f32_e32 v117, v117, v165
	v_mul_f32_e32 v118, v118, v123
	v_mul_f32_e32 v119, v119, v149
	v_mul_f32_e32 v120, v120, v160
	v_mul_f32_e32 v121, v121, v161
	v_mul_f32_e32 v123, v114, v162
	v_mul_f32_e32 v149, v115, v163
	v_mul_f32_e32 v160, v116, v164
	v_cvt_pk_bf16_f32 v114, v118, v119
	v_cvt_pk_bf16_f32 v115, v120, v121
	v_cvt_pk_bf16_f32 v116, v123, v149
	v_cvt_pk_bf16_f32 v117, v160, v117
	global_store_dwordx4 v[170:171], v[114:117], off offset:256 sc0 sc1
	global_load_dwordx4 v[114:117], v[168:169], off offset:256
	v_ashrrev_i32_e32 v167, 31, v166
	v_lshlrev_b64 v[158:159], 12, v[166:167]
	v_or_b32_e32 v122, 32, v148
	v_lshl_add_u64 v[158:159], s[6:7], 0, v[158:159]
	v_mad_i64_i32 v[128:129], s[24:25], v122, s45, v[150:151]
	v_lshl_add_u64 v[158:159], v[158:159], 0, v[146:147]
	v_lshl_add_u64 v[128:129], v[128:129], 0, v[146:147]
	s_waitcnt vmcnt(2)
	v_lshlrev_b32_e32 v118, 16, v124
	v_and_b32_e32 v119, 0xffff0000, v124
	v_lshlrev_b32_e32 v123, 16, v126
	v_and_b32_e32 v124, 0xffff0000, v126
	v_and_b32_e32 v126, 0xffff0000, v127
	v_lshlrev_b32_e32 v120, 16, v125
	v_and_b32_e32 v121, 0xffff0000, v125
	v_lshlrev_b32_e32 v125, 16, v127
	v_mul_f32_e32 v126, 0xbfb8aa3b, v126
	v_mul_f32_e32 v118, 0xbfb8aa3b, v118
	v_mul_f32_e32 v119, 0xbfb8aa3b, v119
	v_mul_f32_e32 v120, 0xbfb8aa3b, v120
	v_mul_f32_e32 v121, 0xbfb8aa3b, v121
	v_mul_f32_e32 v123, 0xbfb8aa3b, v123
	v_mul_f32_e32 v124, 0xbfb8aa3b, v124
	v_mul_f32_e32 v125, 0xbfb8aa3b, v125
	v_exp_f32_e32 v126, v126
	v_exp_f32_e32 v118, v118
	v_exp_f32_e32 v119, v119
	v_exp_f32_e32 v120, v120
	v_exp_f32_e32 v121, v121
	v_exp_f32_e32 v123, v123
	v_exp_f32_e32 v124, v124
	v_exp_f32_e32 v125, v125
	v_add_f32_e32 v126, 1.0, v126
	v_add_f32_e32 v118, 1.0, v118
	v_add_f32_e32 v119, 1.0, v119
	v_add_f32_e32 v120, 1.0, v120
	v_add_f32_e32 v121, 1.0, v121
	v_add_f32_e32 v123, 1.0, v123
	v_add_f32_e32 v124, 1.0, v124
	v_add_f32_e32 v125, 1.0, v125
	v_rcp_f32_e32 v126, v126
	v_rcp_f32_e32 v118, v118
	v_rcp_f32_e32 v119, v119
	v_rcp_f32_e32 v120, v120
	v_rcp_f32_e32 v121, v121
	v_rcp_f32_e32 v123, v123
	v_rcp_f32_e32 v124, v124
	v_rcp_f32_e32 v125, v125
	v_mul_f32_e32 v109, v109, v126
	v_mul_f32_e32 v110, v110, v118
	v_mul_f32_e32 v111, v111, v119
	v_mul_f32_e32 v112, v112, v120
	v_mul_f32_e32 v113, v113, v121
	v_mul_f32_e32 v118, v106, v123
	v_mul_f32_e32 v119, v107, v124
	v_mul_f32_e32 v120, v108, v125
	v_cvt_pk_bf16_f32 v106, v110, v111
	v_cvt_pk_bf16_f32 v107, v112, v113
	v_cvt_pk_bf16_f32 v108, v118, v119
	v_cvt_pk_bf16_f32 v109, v120, v109
	global_store_dwordx4 v[158:159], v[106:109], off sc0 sc1
	global_load_dwordx4 v[106:109], v[128:129], off
	s_waitcnt vmcnt(2)
	v_lshlrev_b32_e32 v110, 16, v114
	v_and_b32_e32 v111, 0xffff0000, v114
	v_lshlrev_b32_e32 v112, 16, v115
	v_and_b32_e32 v113, 0xffff0000, v115
	v_lshlrev_b32_e32 v114, 16, v116
	v_and_b32_e32 v115, 0xffff0000, v116
	v_lshlrev_b32_e32 v116, 16, v117
	v_and_b32_e32 v117, 0xffff0000, v117
	v_mul_f32_e32 v117, 0xbfb8aa3b, v117
	v_mul_f32_e32 v110, 0xbfb8aa3b, v110
	v_mul_f32_e32 v111, 0xbfb8aa3b, v111
	v_mul_f32_e32 v112, 0xbfb8aa3b, v112
	v_mul_f32_e32 v113, 0xbfb8aa3b, v113
	v_mul_f32_e32 v114, 0xbfb8aa3b, v114
	v_mul_f32_e32 v115, 0xbfb8aa3b, v115
	v_mul_f32_e32 v116, 0xbfb8aa3b, v116
	v_exp_f32_e32 v117, v117
	v_exp_f32_e32 v110, v110
	v_exp_f32_e32 v111, v111
	v_exp_f32_e32 v112, v112
	v_exp_f32_e32 v113, v113
	v_exp_f32_e32 v114, v114
	v_exp_f32_e32 v115, v115
	v_exp_f32_e32 v116, v116
	v_add_f32_e32 v117, 1.0, v117
	v_add_f32_e32 v110, 1.0, v110
	v_add_f32_e32 v111, 1.0, v111
	v_add_f32_e32 v112, 1.0, v112
	v_add_f32_e32 v113, 1.0, v113
	v_add_f32_e32 v114, 1.0, v114
	v_add_f32_e32 v115, 1.0, v115
	v_add_f32_e32 v116, 1.0, v116
	v_rcp_f32_e32 v117, v117
	v_rcp_f32_e32 v110, v110
	v_rcp_f32_e32 v111, v111
	v_rcp_f32_e32 v112, v112
	v_rcp_f32_e32 v113, v113
	v_rcp_f32_e32 v114, v114
	v_rcp_f32_e32 v115, v115
	v_rcp_f32_e32 v116, v116
	v_mul_f32_e32 v101, v101, v117
	v_mul_f32_e32 v102, v102, v110
	v_mul_f32_e32 v103, v103, v111
	v_mul_f32_e32 v104, v104, v112
	v_mul_f32_e32 v105, v105, v113
	v_mul_f32_e32 v110, v98, v114
	v_mul_f32_e32 v111, v99, v115
	v_mul_f32_e32 v112, v100, v116
	v_cvt_pk_bf16_f32 v98, v102, v103
	v_cvt_pk_bf16_f32 v99, v104, v105
	v_cvt_pk_bf16_f32 v100, v110, v111
	v_cvt_pk_bf16_f32 v101, v112, v101
	global_store_dwordx4 v[158:159], v[98:101], off offset:256 sc0 sc1
	global_load_dwordx4 v[98:101], v[128:129], off offset:256
	v_ashrrev_i32_e32 v123, 31, v122
	s_waitcnt vmcnt(2)
	v_and_b32_e32 v103, 0xffff0000, v106
	v_mul_f32_e32 v103, 0xbfb8aa3b, v103
	v_lshlrev_b32_e32 v102, 16, v106
	v_exp_f32_e32 v103, v103
	v_lshlrev_b32_e32 v104, 16, v107
	v_lshlrev_b32_e32 v106, 16, v108
	v_mul_f32_e32 v102, 0xbfb8aa3b, v102
	v_mul_f32_e32 v104, 0xbfb8aa3b, v104
	v_mul_f32_e32 v106, 0xbfb8aa3b, v106
	v_exp_f32_e32 v102, v102
	v_and_b32_e32 v105, 0xffff0000, v107
	v_and_b32_e32 v107, 0xffff0000, v108
	v_lshlrev_b32_e32 v108, 16, v109
	v_and_b32_e32 v109, 0xffff0000, v109
	v_exp_f32_e32 v104, v104
	v_exp_f32_e32 v106, v106
	v_mul_f32_e32 v105, 0xbfb8aa3b, v105
	v_mul_f32_e32 v107, 0xbfb8aa3b, v107
	v_mul_f32_e32 v109, 0xbfb8aa3b, v109
	v_add_f32_e32 v103, 1.0, v103
	v_mul_f32_e32 v108, 0xbfb8aa3b, v108
	v_exp_f32_e32 v105, v105
	v_exp_f32_e32 v107, v107
	v_exp_f32_e32 v109, v109
	v_rcp_f32_e32 v103, v103
	v_exp_f32_e32 v108, v108
	v_add_f32_e32 v102, 1.0, v102
	v_add_f32_e32 v104, 1.0, v104
	v_add_f32_e32 v106, 1.0, v106
	v_rcp_f32_e32 v102, v102
	v_rcp_f32_e32 v104, v104
	v_rcp_f32_e32 v106, v106
	v_add_f32_e32 v105, 1.0, v105
	v_add_f32_e32 v107, 1.0, v107
	v_mul_f32_e32 v95, v95, v103
	v_add_f32_e32 v103, 1.0, v109
	v_add_f32_e32 v108, 1.0, v108
	v_rcp_f32_e32 v105, v105
	v_rcp_f32_e32 v107, v107
	v_rcp_f32_e32 v103, v103
	v_mul_f32_e32 v94, v94, v102
	v_rcp_f32_e32 v102, v108
	v_mul_f32_e32 v96, v96, v104
	v_mul_f32_e32 v104, v90, v106
	v_cvt_pk_bf16_f32 v90, v94, v95
	v_lshlrev_b64 v[94:95], 12, v[122:123]
	v_lshl_add_u64 v[94:95], s[6:7], 0, v[94:95]
	v_mul_f32_e32 v97, v97, v105
	v_mul_f32_e32 v105, v91, v107
	v_mul_f32_e32 v93, v93, v103
	v_cvt_pk_bf16_f32 v91, v96, v97
	v_lshl_add_u64 v[94:95], v[94:95], 0, v[146:147]
	v_or_b32_e32 v96, 48, v148
	v_mul_f32_e32 v102, v92, v102
	v_cvt_pk_bf16_f32 v92, v104, v105
	v_cvt_pk_bf16_f32 v93, v102, v93
	global_store_dwordx4 v[94:95], v[90:93], off sc0 sc1
	s_waitcnt vmcnt(1)
	v_lshlrev_b32_e32 v106, 16, v101
	v_and_b32_e32 v101, 0xffff0000, v101
	v_mad_i64_i32 v[90:91], s[24:25], v96, s45, v[150:151]
	v_lshl_add_u64 v[102:103], v[90:91], 0, v[146:147]
	global_load_dwordx4 v[90:93], v[102:103], off
	v_lshlrev_b32_e32 v97, 16, v98
	v_and_b32_e32 v98, 0xffff0000, v98
	v_lshlrev_b32_e32 v104, 16, v99
	v_and_b32_e32 v99, 0xffff0000, v99
	v_lshlrev_b32_e32 v105, 16, v100
	v_and_b32_e32 v100, 0xffff0000, v100
	v_mul_f32_e32 v101, 0xbfb8aa3b, v101
	v_mul_f32_e32 v97, 0xbfb8aa3b, v97
	v_mul_f32_e32 v98, 0xbfb8aa3b, v98
	v_mul_f32_e32 v104, 0xbfb8aa3b, v104
	v_mul_f32_e32 v99, 0xbfb8aa3b, v99
	v_mul_f32_e32 v105, 0xbfb8aa3b, v105
	v_mul_f32_e32 v100, 0xbfb8aa3b, v100
	v_mul_f32_e32 v106, 0xbfb8aa3b, v106
	v_exp_f32_e32 v101, v101
	v_exp_f32_e32 v97, v97
	v_exp_f32_e32 v98, v98
	v_exp_f32_e32 v104, v104
	v_exp_f32_e32 v99, v99
	v_exp_f32_e32 v105, v105
	v_exp_f32_e32 v100, v100
	v_exp_f32_e32 v106, v106
	v_add_f32_e32 v101, 1.0, v101
	v_add_f32_e32 v97, 1.0, v97
	v_add_f32_e32 v98, 1.0, v98
	v_add_f32_e32 v104, 1.0, v104
	v_add_f32_e32 v99, 1.0, v99
	v_add_f32_e32 v105, 1.0, v105
	v_add_f32_e32 v100, 1.0, v100
	v_add_f32_e32 v106, 1.0, v106
	v_rcp_f32_e32 v101, v101
	v_rcp_f32_e32 v97, v97
	v_rcp_f32_e32 v98, v98
	v_rcp_f32_e32 v104, v104
	v_rcp_f32_e32 v99, v99
	v_rcp_f32_e32 v105, v105
	v_rcp_f32_e32 v100, v100
	v_rcp_f32_e32 v106, v106
	v_mul_f32_e32 v85, v85, v101
	v_mul_f32_e32 v86, v86, v97
	v_mul_f32_e32 v87, v87, v98
	v_mul_f32_e32 v88, v88, v104
	v_mul_f32_e32 v89, v89, v99
	v_mul_f32_e32 v97, v82, v105
	v_mul_f32_e32 v98, v83, v100
	v_mul_f32_e32 v99, v84, v106
	v_cvt_pk_bf16_f32 v82, v86, v87
	v_cvt_pk_bf16_f32 v83, v88, v89
	v_cvt_pk_bf16_f32 v84, v97, v98
	v_cvt_pk_bf16_f32 v85, v99, v85
	global_store_dwordx4 v[94:95], v[82:85], off offset:256 sc0 sc1
	global_load_dwordx4 v[82:85], v[102:103], off offset:256
	v_ashrrev_i32_e32 v97, 31, v96
	s_waitcnt vmcnt(2)
	v_and_b32_e32 v87, 0xffff0000, v90
	v_lshlrev_b32_e32 v88, 16, v91
	v_lshlrev_b32_e32 v86, 16, v90
	v_mul_f32_e32 v87, 0xbfb8aa3b, v87
	v_mul_f32_e32 v88, 0xbfb8aa3b, v88
	v_mul_f32_e32 v86, 0xbfb8aa3b, v86
	v_exp_f32_e32 v87, v87
	v_exp_f32_e32 v88, v88
	v_exp_f32_e32 v86, v86
	v_and_b32_e32 v89, 0xffff0000, v91
	v_add_f32_e32 v87, 1.0, v87
	v_add_f32_e32 v88, 1.0, v88
	v_mul_f32_e32 v89, 0xbfb8aa3b, v89
	v_add_f32_e32 v86, 1.0, v86
	v_rcp_f32_e32 v87, v87
	v_rcp_f32_e32 v88, v88
	v_rcp_f32_e32 v86, v86
	v_exp_f32_e32 v89, v89
	v_mul_f32_e32 v79, v79, v87
	v_mul_f32_e32 v80, v80, v88
	v_lshlrev_b32_e32 v87, 16, v92
	v_and_b32_e32 v88, 0xffff0000, v92
	v_mul_f32_e32 v78, v78, v86
	v_add_f32_e32 v86, 1.0, v89
	v_mul_f32_e32 v87, 0xbfb8aa3b, v87
	v_mul_f32_e32 v88, 0xbfb8aa3b, v88
	v_rcp_f32_e32 v86, v86
	v_exp_f32_e32 v87, v87
	v_exp_f32_e32 v88, v88
	v_and_b32_e32 v89, 0xffff0000, v93
	v_mul_f32_e32 v81, v81, v86
	v_add_f32_e32 v86, 1.0, v87
	v_add_f32_e32 v87, 1.0, v88
	v_lshlrev_b32_e32 v88, 16, v93
	v_mul_f32_e32 v89, 0xbfb8aa3b, v89
	v_mul_f32_e32 v88, 0xbfb8aa3b, v88
	v_exp_f32_e32 v89, v89
	v_exp_f32_e32 v88, v88
	v_rcp_f32_e32 v86, v86
	v_rcp_f32_e32 v87, v87
	v_add_f32_e32 v89, 1.0, v89
	v_add_f32_e32 v88, 1.0, v88
	v_rcp_f32_e32 v89, v89
	v_rcp_f32_e32 v88, v88
	v_mul_f32_e32 v86, v74, v86
	v_cvt_pk_bf16_f32 v74, v78, v79
	v_lshlrev_b64 v[78:79], 12, v[96:97]
	v_lshl_add_u64 v[78:79], s[6:7], 0, v[78:79]
	v_mul_f32_e32 v87, v75, v87
	v_mul_f32_e32 v77, v77, v89
	v_cvt_pk_bf16_f32 v75, v80, v81
	v_lshl_add_u64 v[78:79], v[78:79], 0, v[146:147]
	v_add_u32_e32 v80, 0x80, v148
	v_mul_f32_e32 v88, v76, v88
	v_cvt_pk_bf16_f32 v76, v86, v87
	v_cvt_pk_bf16_f32 v77, v88, v77
	global_store_dwordx4 v[78:79], v[74:77], off sc0 sc1
	s_waitcnt vmcnt(1)
	v_lshlrev_b32_e32 v81, 16, v82
	v_and_b32_e32 v82, 0xffff0000, v82
	v_mad_i64_i32 v[74:75], s[24:25], v80, s45, v[150:151]
	v_lshl_add_u64 v[86:87], v[74:75], 0, v[146:147]
	global_load_dwordx4 v[74:77], v[86:87], off
	v_mul_f32_e32 v81, 0xbfb8aa3b, v81
	v_mul_f32_e32 v82, 0xbfb8aa3b, v82
	v_exp_f32_e32 v81, v81
	v_exp_f32_e32 v82, v82
	v_lshlrev_b32_e32 v88, 16, v83
	v_and_b32_e32 v83, 0xffff0000, v83
	v_add_f32_e32 v81, 1.0, v81
	v_add_f32_e32 v82, 1.0, v82
	v_mul_f32_e32 v83, 0xbfb8aa3b, v83
	v_rcp_f32_e32 v81, v81
	v_rcp_f32_e32 v82, v82
	v_exp_f32_e32 v83, v83
	v_mul_f32_e32 v88, 0xbfb8aa3b, v88
	v_mul_f32_e32 v70, v70, v81
	v_mul_f32_e32 v71, v71, v82
	v_add_f32_e32 v81, 1.0, v83
	v_lshlrev_b32_e32 v82, 16, v84
	v_and_b32_e32 v83, 0xffff0000, v84
	v_mul_f32_e32 v82, 0xbfb8aa3b, v82
	v_mul_f32_e32 v83, 0xbfb8aa3b, v83
	v_rcp_f32_e32 v81, v81
	v_exp_f32_e32 v82, v82
	v_exp_f32_e32 v83, v83
	v_and_b32_e32 v84, 0xffff0000, v85
	v_mul_f32_e32 v73, v73, v81
	v_add_f32_e32 v81, 1.0, v82
	v_add_f32_e32 v82, 1.0, v83
	v_lshlrev_b32_e32 v83, 16, v85
	v_mul_f32_e32 v84, 0xbfb8aa3b, v84
	v_mul_f32_e32 v83, 0xbfb8aa3b, v83
	v_exp_f32_e32 v84, v84
	v_exp_f32_e32 v88, v88
	v_exp_f32_e32 v83, v83
	v_rcp_f32_e32 v81, v81
	v_add_f32_e32 v84, 1.0, v84
	v_add_f32_e32 v88, 1.0, v88
	v_add_f32_e32 v83, 1.0, v83
	v_rcp_f32_e32 v84, v84
	v_rcp_f32_e32 v88, v88
	v_rcp_f32_e32 v82, v82
	v_rcp_f32_e32 v83, v83
	v_mul_f32_e32 v69, v69, v84
	v_mul_f32_e32 v72, v72, v88
	v_mul_f32_e32 v81, v66, v81
	v_mul_f32_e32 v82, v67, v82
	v_mul_f32_e32 v83, v68, v83
	v_cvt_pk_bf16_f32 v66, v70, v71
	v_cvt_pk_bf16_f32 v67, v72, v73
	v_cvt_pk_bf16_f32 v68, v81, v82
	v_cvt_pk_bf16_f32 v69, v83, v69
	global_store_dwordx4 v[78:79], v[66:69], off offset:256 sc0 sc1
	global_load_dwordx4 v[66:69], v[86:87], off offset:256
	v_ashrrev_i32_e32 v81, 31, v80
	s_waitcnt vmcnt(2)
	v_and_b32_e32 v71, 0xffff0000, v74
	v_lshlrev_b32_e32 v72, 16, v75
	v_lshlrev_b32_e32 v70, 16, v74
	v_mul_f32_e32 v71, 0xbfb8aa3b, v71
	v_mul_f32_e32 v72, 0xbfb8aa3b, v72
	v_mul_f32_e32 v70, 0xbfb8aa3b, v70
	v_exp_f32_e32 v71, v71
	v_exp_f32_e32 v72, v72
	v_exp_f32_e32 v70, v70
	v_and_b32_e32 v73, 0xffff0000, v75
	v_add_f32_e32 v71, 1.0, v71
	v_add_f32_e32 v72, 1.0, v72
	v_add_f32_e32 v70, 1.0, v70
	v_rcp_f32_e32 v71, v71
	v_rcp_f32_e32 v72, v72
	v_mul_f32_e32 v73, 0xbfb8aa3b, v73
	v_rcp_f32_e32 v70, v70
	v_exp_f32_e32 v73, v73
	v_mul_f32_e32 v63, v63, v71
	v_mul_f32_e32 v64, v64, v72
	v_lshlrev_b32_e32 v71, 16, v76
	v_and_b32_e32 v72, 0xffff0000, v76
	v_mul_f32_e32 v62, v62, v70
	v_add_f32_e32 v70, 1.0, v73
	v_mul_f32_e32 v71, 0xbfb8aa3b, v71
	v_mul_f32_e32 v72, 0xbfb8aa3b, v72
	v_rcp_f32_e32 v70, v70
	v_exp_f32_e32 v71, v71
	v_exp_f32_e32 v72, v72
	v_and_b32_e32 v73, 0xffff0000, v77
	v_mul_f32_e32 v65, v65, v70
	v_add_f32_e32 v70, 1.0, v71
	v_add_f32_e32 v71, 1.0, v72
	v_lshlrev_b32_e32 v72, 16, v77
	v_mul_f32_e32 v73, 0xbfb8aa3b, v73
	v_mul_f32_e32 v72, 0xbfb8aa3b, v72
	v_exp_f32_e32 v73, v73
	v_exp_f32_e32 v72, v72
	v_rcp_f32_e32 v70, v70
	v_rcp_f32_e32 v71, v71
	v_add_f32_e32 v73, 1.0, v73
	v_add_f32_e32 v72, 1.0, v72
	v_rcp_f32_e32 v73, v73
	v_rcp_f32_e32 v72, v72
	v_mul_f32_e32 v70, v58, v70
	v_cvt_pk_bf16_f32 v58, v62, v63
	v_lshlrev_b64 v[62:63], 12, v[80:81]
	v_lshl_add_u64 v[62:63], s[6:7], 0, v[62:63]
	v_mul_f32_e32 v71, v59, v71
	v_mul_f32_e32 v61, v61, v73
	v_cvt_pk_bf16_f32 v59, v64, v65
	v_lshl_add_u64 v[62:63], v[62:63], 0, v[146:147]
	v_add_u32_e32 v64, 0x90, v148
	v_mul_f32_e32 v72, v60, v72
	v_cvt_pk_bf16_f32 v60, v70, v71
	v_cvt_pk_bf16_f32 v61, v72, v61
	global_store_dwordx4 v[62:63], v[58:61], off sc0 sc1
	s_waitcnt vmcnt(1)
	v_lshlrev_b32_e32 v65, 16, v66
	v_and_b32_e32 v66, 0xffff0000, v66
	v_mad_i64_i32 v[58:59], s[24:25], v64, s45, v[150:151]
	v_lshl_add_u64 v[70:71], v[58:59], 0, v[146:147]
	global_load_dwordx4 v[58:61], v[70:71], off
	v_mul_f32_e32 v65, 0xbfb8aa3b, v65
	v_mul_f32_e32 v66, 0xbfb8aa3b, v66
	v_exp_f32_e32 v65, v65
	v_exp_f32_e32 v66, v66
	v_lshlrev_b32_e32 v72, 16, v67
	v_and_b32_e32 v67, 0xffff0000, v67
	v_add_f32_e32 v65, 1.0, v65
	v_add_f32_e32 v66, 1.0, v66
	v_mul_f32_e32 v67, 0xbfb8aa3b, v67
	v_rcp_f32_e32 v65, v65
	v_rcp_f32_e32 v66, v66
	v_exp_f32_e32 v67, v67
	v_mul_f32_e32 v72, 0xbfb8aa3b, v72
	v_mul_f32_e32 v54, v54, v65
	v_mul_f32_e32 v55, v55, v66
	v_add_f32_e32 v65, 1.0, v67
	v_lshlrev_b32_e32 v66, 16, v68
	v_and_b32_e32 v67, 0xffff0000, v68
	v_mul_f32_e32 v66, 0xbfb8aa3b, v66
	v_mul_f32_e32 v67, 0xbfb8aa3b, v67
	v_rcp_f32_e32 v65, v65
	v_exp_f32_e32 v66, v66
	v_exp_f32_e32 v67, v67
	v_and_b32_e32 v68, 0xffff0000, v69
	v_mul_f32_e32 v57, v57, v65
	v_add_f32_e32 v65, 1.0, v66
	v_add_f32_e32 v66, 1.0, v67
	v_lshlrev_b32_e32 v67, 16, v69
	v_mul_f32_e32 v68, 0xbfb8aa3b, v68
	v_mul_f32_e32 v67, 0xbfb8aa3b, v67
	v_exp_f32_e32 v68, v68
	v_exp_f32_e32 v72, v72
	v_exp_f32_e32 v67, v67
	v_rcp_f32_e32 v65, v65
	v_add_f32_e32 v68, 1.0, v68
	v_add_f32_e32 v72, 1.0, v72
	v_add_f32_e32 v67, 1.0, v67
	v_rcp_f32_e32 v68, v68
	v_rcp_f32_e32 v72, v72
	v_rcp_f32_e32 v66, v66
	v_rcp_f32_e32 v67, v67
	v_mul_f32_e32 v53, v53, v68
	v_mul_f32_e32 v56, v56, v72
	v_mul_f32_e32 v65, v50, v65
	v_mul_f32_e32 v66, v51, v66
	v_mul_f32_e32 v67, v52, v67
	v_cvt_pk_bf16_f32 v50, v54, v55
	v_cvt_pk_bf16_f32 v51, v56, v57
	v_cvt_pk_bf16_f32 v52, v65, v66
	v_cvt_pk_bf16_f32 v53, v67, v53
	global_store_dwordx4 v[62:63], v[50:53], off offset:256 sc0 sc1
	global_load_dwordx4 v[50:53], v[70:71], off offset:256
	v_ashrrev_i32_e32 v65, 31, v64
	s_waitcnt vmcnt(2)
	v_and_b32_e32 v55, 0xffff0000, v58
	v_lshlrev_b32_e32 v56, 16, v59
	v_lshlrev_b32_e32 v54, 16, v58
	v_mul_f32_e32 v55, 0xbfb8aa3b, v55
	v_mul_f32_e32 v56, 0xbfb8aa3b, v56
	v_mul_f32_e32 v54, 0xbfb8aa3b, v54
	v_exp_f32_e32 v55, v55
	v_exp_f32_e32 v56, v56
	v_exp_f32_e32 v54, v54
	v_and_b32_e32 v57, 0xffff0000, v59
	v_add_f32_e32 v55, 1.0, v55
	v_add_f32_e32 v56, 1.0, v56
	v_add_f32_e32 v54, 1.0, v54
	v_rcp_f32_e32 v55, v55
	v_rcp_f32_e32 v56, v56
	v_mul_f32_e32 v57, 0xbfb8aa3b, v57
	v_rcp_f32_e32 v54, v54
	v_exp_f32_e32 v57, v57
	v_mul_f32_e32 v47, v47, v55
	v_mul_f32_e32 v48, v48, v56
	v_lshlrev_b32_e32 v55, 16, v60
	v_and_b32_e32 v56, 0xffff0000, v60
	v_mul_f32_e32 v46, v46, v54
	v_add_f32_e32 v54, 1.0, v57
	v_mul_f32_e32 v55, 0xbfb8aa3b, v55
	v_mul_f32_e32 v56, 0xbfb8aa3b, v56
	v_rcp_f32_e32 v54, v54
	v_exp_f32_e32 v55, v55
	v_exp_f32_e32 v56, v56
	v_and_b32_e32 v57, 0xffff0000, v61
	v_mul_f32_e32 v49, v49, v54
	v_add_f32_e32 v54, 1.0, v55
	v_add_f32_e32 v55, 1.0, v56
	v_lshlrev_b32_e32 v56, 16, v61
	v_mul_f32_e32 v57, 0xbfb8aa3b, v57
	v_mul_f32_e32 v56, 0xbfb8aa3b, v56
	v_exp_f32_e32 v57, v57
	v_exp_f32_e32 v56, v56
	v_rcp_f32_e32 v54, v54
	v_rcp_f32_e32 v55, v55
	v_add_f32_e32 v57, 1.0, v57
	v_add_f32_e32 v56, 1.0, v56
	v_rcp_f32_e32 v57, v57
	v_rcp_f32_e32 v56, v56
	v_mul_f32_e32 v54, v42, v54
	v_cvt_pk_bf16_f32 v42, v46, v47
	v_lshlrev_b64 v[46:47], 12, v[64:65]
	v_lshl_add_u64 v[46:47], s[6:7], 0, v[46:47]
	v_mul_f32_e32 v55, v43, v55
	v_mul_f32_e32 v45, v45, v57
	v_cvt_pk_bf16_f32 v43, v48, v49
	v_lshl_add_u64 v[46:47], v[46:47], 0, v[146:147]
	v_add_u32_e32 v48, 0xa0, v148
	v_mul_f32_e32 v56, v44, v56
	v_cvt_pk_bf16_f32 v44, v54, v55
	v_cvt_pk_bf16_f32 v45, v56, v45
	global_store_dwordx4 v[46:47], v[42:45], off sc0 sc1
	s_waitcnt vmcnt(1)
	v_lshlrev_b32_e32 v49, 16, v50
	v_and_b32_e32 v50, 0xffff0000, v50
	v_mad_i64_i32 v[42:43], s[24:25], v48, s45, v[150:151]
	v_lshl_add_u64 v[54:55], v[42:43], 0, v[146:147]
	global_load_dwordx4 v[42:45], v[54:55], off
	v_mul_f32_e32 v49, 0xbfb8aa3b, v49
	v_mul_f32_e32 v50, 0xbfb8aa3b, v50
	v_exp_f32_e32 v49, v49
	v_exp_f32_e32 v50, v50
	v_lshlrev_b32_e32 v56, 16, v51
	v_and_b32_e32 v51, 0xffff0000, v51
	v_add_f32_e32 v49, 1.0, v49
	v_add_f32_e32 v50, 1.0, v50
	v_mul_f32_e32 v51, 0xbfb8aa3b, v51
	v_rcp_f32_e32 v49, v49
	v_rcp_f32_e32 v50, v50
	v_exp_f32_e32 v51, v51
	v_mul_f32_e32 v56, 0xbfb8aa3b, v56
	v_mul_f32_e32 v38, v38, v49
	v_mul_f32_e32 v39, v39, v50
	v_add_f32_e32 v49, 1.0, v51
	v_lshlrev_b32_e32 v50, 16, v52
	v_and_b32_e32 v51, 0xffff0000, v52
	v_mul_f32_e32 v50, 0xbfb8aa3b, v50
	v_mul_f32_e32 v51, 0xbfb8aa3b, v51
	v_rcp_f32_e32 v49, v49
	v_exp_f32_e32 v50, v50
	v_exp_f32_e32 v51, v51
	v_and_b32_e32 v52, 0xffff0000, v53
	v_mul_f32_e32 v41, v41, v49
	v_add_f32_e32 v49, 1.0, v50
	v_add_f32_e32 v50, 1.0, v51
	v_lshlrev_b32_e32 v51, 16, v53
	v_mul_f32_e32 v52, 0xbfb8aa3b, v52
	v_mul_f32_e32 v51, 0xbfb8aa3b, v51
	v_exp_f32_e32 v52, v52
	v_exp_f32_e32 v56, v56
	v_exp_f32_e32 v51, v51
	v_rcp_f32_e32 v49, v49
	v_add_f32_e32 v52, 1.0, v52
	v_add_f32_e32 v56, 1.0, v56
	v_add_f32_e32 v51, 1.0, v51
	v_rcp_f32_e32 v52, v52
	v_rcp_f32_e32 v56, v56
	v_rcp_f32_e32 v50, v50
	v_rcp_f32_e32 v51, v51
	v_mul_f32_e32 v37, v37, v52
	v_mul_f32_e32 v40, v40, v56
	v_mul_f32_e32 v49, v34, v49
	v_mul_f32_e32 v50, v35, v50
	v_mul_f32_e32 v51, v36, v51
	v_cvt_pk_bf16_f32 v34, v38, v39
	v_cvt_pk_bf16_f32 v35, v40, v41
	v_cvt_pk_bf16_f32 v36, v49, v50
	v_cvt_pk_bf16_f32 v37, v51, v37
	global_store_dwordx4 v[46:47], v[34:37], off offset:256 sc0 sc1
	global_load_dwordx4 v[34:37], v[54:55], off offset:256
	v_ashrrev_i32_e32 v49, 31, v48
	s_waitcnt vmcnt(2)
	v_and_b32_e32 v39, 0xffff0000, v42
	v_lshlrev_b32_e32 v40, 16, v43
	v_lshlrev_b32_e32 v38, 16, v42
	v_mul_f32_e32 v39, 0xbfb8aa3b, v39
	v_mul_f32_e32 v40, 0xbfb8aa3b, v40
	v_mul_f32_e32 v38, 0xbfb8aa3b, v38
	v_exp_f32_e32 v39, v39
	v_exp_f32_e32 v40, v40
	v_exp_f32_e32 v38, v38
	v_and_b32_e32 v41, 0xffff0000, v43
	v_add_f32_e32 v39, 1.0, v39
	v_add_f32_e32 v40, 1.0, v40
	v_add_f32_e32 v38, 1.0, v38
	v_rcp_f32_e32 v39, v39
	v_rcp_f32_e32 v40, v40
	v_mul_f32_e32 v41, 0xbfb8aa3b, v41
	v_rcp_f32_e32 v38, v38
	v_exp_f32_e32 v41, v41
	v_mul_f32_e32 v31, v31, v39
	v_mul_f32_e32 v32, v32, v40
	v_lshlrev_b32_e32 v39, 16, v44
	v_and_b32_e32 v40, 0xffff0000, v44
	v_mul_f32_e32 v30, v30, v38
	v_add_f32_e32 v38, 1.0, v41
	v_mul_f32_e32 v39, 0xbfb8aa3b, v39
	v_mul_f32_e32 v40, 0xbfb8aa3b, v40
	v_rcp_f32_e32 v38, v38
	v_exp_f32_e32 v39, v39
	v_exp_f32_e32 v40, v40
	v_and_b32_e32 v41, 0xffff0000, v45
	v_mul_f32_e32 v33, v33, v38
	v_add_f32_e32 v38, 1.0, v39
	v_add_f32_e32 v39, 1.0, v40
	v_lshlrev_b32_e32 v40, 16, v45
	v_mul_f32_e32 v41, 0xbfb8aa3b, v41
	v_mul_f32_e32 v40, 0xbfb8aa3b, v40
	v_exp_f32_e32 v41, v41
	v_exp_f32_e32 v40, v40
	v_rcp_f32_e32 v38, v38
	v_rcp_f32_e32 v39, v39
	v_add_f32_e32 v41, 1.0, v41
	v_add_f32_e32 v40, 1.0, v40
	v_rcp_f32_e32 v41, v41
	v_rcp_f32_e32 v40, v40
	v_mul_f32_e32 v38, v26, v38
	v_cvt_pk_bf16_f32 v26, v30, v31
	v_lshlrev_b64 v[30:31], 12, v[48:49]
	v_lshl_add_u64 v[30:31], s[6:7], 0, v[30:31]
	v_mul_f32_e32 v39, v27, v39
	v_mul_f32_e32 v29, v29, v41
	v_cvt_pk_bf16_f32 v27, v32, v33
	v_lshl_add_u64 v[30:31], v[30:31], 0, v[146:147]
	v_add_u32_e32 v32, 0xb0, v148
	v_mul_f32_e32 v40, v28, v40
	v_cvt_pk_bf16_f32 v28, v38, v39
	v_cvt_pk_bf16_f32 v29, v40, v29
	global_store_dwordx4 v[30:31], v[26:29], off sc0 sc1
	s_waitcnt vmcnt(1)
	v_lshlrev_b32_e32 v33, 16, v34
	v_and_b32_e32 v34, 0xffff0000, v34
	v_mad_i64_i32 v[26:27], s[24:25], v32, s45, v[150:151]
	v_lshl_add_u64 v[38:39], v[26:27], 0, v[146:147]
	global_load_dwordx4 v[26:29], v[38:39], off
	v_mul_f32_e32 v33, 0xbfb8aa3b, v33
	v_mul_f32_e32 v34, 0xbfb8aa3b, v34
	v_exp_f32_e32 v33, v33
	v_exp_f32_e32 v34, v34
	v_lshlrev_b32_e32 v40, 16, v35
	v_and_b32_e32 v35, 0xffff0000, v35
	v_add_f32_e32 v33, 1.0, v33
	v_add_f32_e32 v34, 1.0, v34
	v_mul_f32_e32 v35, 0xbfb8aa3b, v35
	v_rcp_f32_e32 v33, v33
	v_rcp_f32_e32 v34, v34
	v_exp_f32_e32 v35, v35
	v_mul_f32_e32 v40, 0xbfb8aa3b, v40
	v_mul_f32_e32 v22, v22, v33
	v_mul_f32_e32 v23, v23, v34
	v_add_f32_e32 v33, 1.0, v35
	v_lshlrev_b32_e32 v34, 16, v36
	v_and_b32_e32 v35, 0xffff0000, v36
	v_mul_f32_e32 v34, 0xbfb8aa3b, v34
	v_mul_f32_e32 v35, 0xbfb8aa3b, v35
	v_rcp_f32_e32 v33, v33
	v_exp_f32_e32 v34, v34
	v_exp_f32_e32 v35, v35
	v_and_b32_e32 v36, 0xffff0000, v37
	v_mul_f32_e32 v25, v25, v33
	v_add_f32_e32 v33, 1.0, v34
	v_add_f32_e32 v34, 1.0, v35
	v_lshlrev_b32_e32 v35, 16, v37
	v_mul_f32_e32 v36, 0xbfb8aa3b, v36
	v_mul_f32_e32 v35, 0xbfb8aa3b, v35
	v_exp_f32_e32 v36, v36
	v_exp_f32_e32 v40, v40
	v_exp_f32_e32 v35, v35
	v_rcp_f32_e32 v33, v33
	v_add_f32_e32 v36, 1.0, v36
	v_add_f32_e32 v40, 1.0, v40
	v_add_f32_e32 v35, 1.0, v35
	v_rcp_f32_e32 v36, v36
	v_rcp_f32_e32 v40, v40
	v_rcp_f32_e32 v34, v34
	v_rcp_f32_e32 v35, v35
	v_mul_f32_e32 v21, v21, v36
	v_mul_f32_e32 v24, v24, v40
	v_mul_f32_e32 v33, v18, v33
	v_mul_f32_e32 v34, v19, v34
	v_mul_f32_e32 v35, v20, v35
	v_cvt_pk_bf16_f32 v18, v22, v23
	v_cvt_pk_bf16_f32 v19, v24, v25
	v_cvt_pk_bf16_f32 v20, v33, v34
	v_cvt_pk_bf16_f32 v21, v35, v21
	global_store_dwordx4 v[30:31], v[18:21], off offset:256 sc0 sc1
	global_load_dwordx4 v[18:21], v[38:39], off offset:256
	v_ashrrev_i32_e32 v33, 31, v32
	s_waitcnt vmcnt(2)
	v_and_b32_e32 v23, 0xffff0000, v26
	v_lshlrev_b32_e32 v24, 16, v27
	v_lshlrev_b32_e32 v22, 16, v26
	v_mul_f32_e32 v23, 0xbfb8aa3b, v23
	v_mul_f32_e32 v24, 0xbfb8aa3b, v24
	v_mul_f32_e32 v22, 0xbfb8aa3b, v22
	v_exp_f32_e32 v23, v23
	v_exp_f32_e32 v24, v24
	v_exp_f32_e32 v22, v22
	v_and_b32_e32 v25, 0xffff0000, v27
	v_add_f32_e32 v23, 1.0, v23
	v_add_f32_e32 v24, 1.0, v24
	v_add_f32_e32 v22, 1.0, v22
	v_rcp_f32_e32 v23, v23
	v_rcp_f32_e32 v24, v24
	v_mul_f32_e32 v25, 0xbfb8aa3b, v25
	v_rcp_f32_e32 v22, v22
	v_exp_f32_e32 v25, v25
	v_mul_f32_e32 v15, v15, v23
	v_mul_f32_e32 v16, v16, v24
	v_lshlrev_b32_e32 v23, 16, v28
	v_and_b32_e32 v24, 0xffff0000, v28
	v_mul_f32_e32 v14, v14, v22
	v_add_f32_e32 v22, 1.0, v25
	v_mul_f32_e32 v23, 0xbfb8aa3b, v23
	v_mul_f32_e32 v24, 0xbfb8aa3b, v24
	v_rcp_f32_e32 v22, v22
	v_exp_f32_e32 v23, v23
	v_exp_f32_e32 v24, v24
	v_and_b32_e32 v25, 0xffff0000, v29
	v_mul_f32_e32 v17, v17, v22
	v_add_f32_e32 v22, 1.0, v23
	v_add_f32_e32 v23, 1.0, v24
	v_lshlrev_b32_e32 v24, 16, v29
	v_mul_f32_e32 v24, 0xbfb8aa3b, v24
	v_mul_f32_e32 v25, 0xbfb8aa3b, v25
	v_exp_f32_e32 v24, v24
	v_exp_f32_e32 v25, v25
	v_rcp_f32_e32 v22, v22
	v_rcp_f32_e32 v23, v23
	v_add_f32_e32 v24, 1.0, v24
	v_add_f32_e32 v25, 1.0, v25
	v_rcp_f32_e32 v24, v24
	v_rcp_f32_e32 v25, v25
	v_mul_f32_e32 v22, v10, v22
	v_cvt_pk_bf16_f32 v10, v14, v15
	v_lshlrev_b64 v[14:15], 12, v[32:33]
	v_lshl_add_u64 v[14:15], s[6:7], 0, v[14:15]
	v_mul_f32_e32 v23, v11, v23
	v_mul_f32_e32 v24, v12, v24
	v_mul_f32_e32 v13, v13, v25
	v_cvt_pk_bf16_f32 v11, v16, v17
	v_cvt_pk_bf16_f32 v12, v22, v23
	v_lshl_add_u64 v[14:15], v[14:15], 0, v[146:147]
	v_cvt_pk_bf16_f32 v13, v24, v13
	global_store_dwordx4 v[14:15], v[10:13], off sc0 sc1
	s_waitcnt vmcnt(1)
	v_lshlrev_b32_e32 v16, 16, v18
	v_mul_f32_e32 v16, 0xbfb8aa3b, v16
	v_and_b32_e32 v11, 0xffff0000, v18
	v_lshlrev_b32_e32 v12, 16, v19
	v_mul_f32_e32 v11, 0xbfb8aa3b, v11
	v_mul_f32_e32 v12, 0xbfb8aa3b, v12
	v_exp_f32_e32 v11, v11
	v_exp_f32_e32 v12, v12
	v_exp_f32_e32 v16, v16
	v_and_b32_e32 v13, 0xffff0000, v19
	v_add_f32_e32 v11, 1.0, v11
	v_add_f32_e32 v12, 1.0, v12
	v_add_f32_e32 v10, 1.0, v16
	v_rcp_f32_e32 v11, v11
	v_rcp_f32_e32 v12, v12
	v_mul_f32_e32 v13, 0xbfb8aa3b, v13
	v_rcp_f32_e32 v10, v10
	v_exp_f32_e32 v13, v13
	v_mul_f32_e32 v7, v7, v11
	v_mul_f32_e32 v8, v8, v12
	v_lshlrev_b32_e32 v11, 16, v20
	v_and_b32_e32 v12, 0xffff0000, v20
	v_mul_f32_e32 v6, v6, v10
	v_add_f32_e32 v10, 1.0, v13
	v_mul_f32_e32 v11, 0xbfb8aa3b, v11
	v_mul_f32_e32 v12, 0xbfb8aa3b, v12
	v_rcp_f32_e32 v10, v10
	v_exp_f32_e32 v11, v11
	v_exp_f32_e32 v12, v12
	v_and_b32_e32 v13, 0xffff0000, v21
	v_mul_f32_e32 v9, v9, v10
	v_add_f32_e32 v10, 1.0, v11
	v_add_f32_e32 v11, 1.0, v12
	v_lshlrev_b32_e32 v12, 16, v21
	v_mul_f32_e32 v13, 0xbfb8aa3b, v13
	v_mul_f32_e32 v12, 0xbfb8aa3b, v12
	v_exp_f32_e32 v13, v13
	v_exp_f32_e32 v12, v12
	v_rcp_f32_e32 v10, v10
	v_rcp_f32_e32 v11, v11
	v_add_f32_e32 v13, 1.0, v13
	v_add_f32_e32 v12, 1.0, v12
	v_rcp_f32_e32 v13, v13
	v_rcp_f32_e32 v12, v12
	v_mul_f32_e32 v10, v2, v10
	v_mul_f32_e32 v11, v3, v11
	v_mul_f32_e32 v5, v5, v13
	v_mul_f32_e32 v12, v4, v12
	v_cvt_pk_bf16_f32 v2, v6, v7
	v_cvt_pk_bf16_f32 v3, v8, v9
	v_cvt_pk_bf16_f32 v4, v10, v11
	v_cvt_pk_bf16_f32 v5, v12, v5
	global_store_dwordx4 v[14:15], v[2:5], off offset:256 sc0 sc1
	s_cbranch_vccnz .LBB0_883
	s_andn2_b64 vcc, exec, s[2:3]
	s_cbranch_vccnz .LBB0_882
	s_barrier
	s_branch .LBB0_882

.LBB0_918:
	v_lshl_or_b32 v146, s53, 8, v156
	v_lshl_add_u32 v148, s22, 8, v1
	v_mov_b64_e32 v[150:151], s[8:9]
	v_ashrrev_i32_e32 v147, 31, v146
	v_mad_i64_i32 v[152:153], s[24:25], v148, s45, v[150:151]
	v_lshlrev_b64 v[146:147], 1, v[146:147]
	v_lshl_add_u64 v[152:153], v[152:153], 0, v[146:147]
	global_load_dwordx4 v[160:163], v[152:153], off
	v_ashrrev_i32_e32 v149, 31, v148
	v_lshlrev_b64 v[172:173], 12, v[148:149]
	v_lshl_add_u64 v[164:165], s[6:7], 0, v[172:173]
	v_lshl_add_u64 v[174:175], v[164:165], 0, v[146:147]
	global_load_dwordx4 v[164:167], v[174:175], off
	global_load_dwordx4 v[168:171], v[152:153], off offset:256
	v_lshl_add_u64 v[172:173], s[2:3], 0, v[172:173]
	v_lshl_add_u64 v[178:179], v[172:173], 0, v[146:147]
	global_load_dwordx4 v[172:175], v[174:175], off offset:256
	v_or_b32_e32 v152, 16, v148
	v_mad_i64_i32 v[176:177], s[24:25], v152, s45, v[150:151]
	v_lshl_add_u64 v[176:177], v[176:177], 0, v[146:147]
	v_ashrrev_i32_e32 v153, 31, v152
	v_lshlrev_b64 v[152:153], 12, v[152:153]
	v_lshl_add_u64 v[180:181], s[6:7], 0, v[152:153]
	s_andn2_b64 vcc, exec, s[4:5]
	s_mov_b64 s[4:5], -1
	s_waitcnt vmcnt(0)
	v_lshlrev_b32_e32 v149, 16, v160
	v_and_b32_e32 v160, 0xffff0000, v160
	v_lshlrev_b32_e32 v182, 16, v161
	v_and_b32_e32 v161, 0xffff0000, v161
	v_lshlrev_b32_e32 v183, 16, v162
	v_and_b32_e32 v162, 0xffff0000, v162
	v_lshlrev_b32_e32 v184, 16, v163
	v_and_b32_e32 v163, 0xffff0000, v163
	v_mul_f32_e32 v149, 0xbfb8aa3b, v149
	v_mul_f32_e32 v160, 0xbfb8aa3b, v160
	v_mul_f32_e32 v182, 0xbfb8aa3b, v182
	v_mul_f32_e32 v161, 0xbfb8aa3b, v161
	v_mul_f32_e32 v183, 0xbfb8aa3b, v183
	v_mul_f32_e32 v162, 0xbfb8aa3b, v162
	v_mul_f32_e32 v184, 0xbfb8aa3b, v184
	v_mul_f32_e32 v163, 0xbfb8aa3b, v163
	v_exp_f32_e32 v149, v149
	v_exp_f32_e32 v160, v160
	v_exp_f32_e32 v182, v182
	v_exp_f32_e32 v161, v161
	v_exp_f32_e32 v183, v183
	v_exp_f32_e32 v162, v162
	v_exp_f32_e32 v184, v184
	v_exp_f32_e32 v163, v163
	v_add_f32_e32 v149, 1.0, v149
	v_add_f32_e32 v160, 1.0, v160
	v_add_f32_e32 v182, 1.0, v182
	v_add_f32_e32 v161, 1.0, v161
	v_add_f32_e32 v183, 1.0, v183
	v_add_f32_e32 v162, 1.0, v162
	v_add_f32_e32 v184, 1.0, v184
	v_add_f32_e32 v163, 1.0, v163
	v_rcp_f32_e32 v149, v149
	v_rcp_f32_e32 v160, v160
	v_rcp_f32_e32 v182, v182
	v_rcp_f32_e32 v161, v161
	v_rcp_f32_e32 v183, v183
	v_rcp_f32_e32 v162, v162
	v_rcp_f32_e32 v184, v184
	v_rcp_f32_e32 v163, v163
	v_lshlrev_b32_e32 v185, 16, v164
	v_and_b32_e32 v164, 0xffff0000, v164
	v_lshlrev_b32_e32 v186, 16, v165
	v_and_b32_e32 v165, 0xffff0000, v165
	v_lshlrev_b32_e32 v187, 16, v166
	v_and_b32_e32 v166, 0xffff0000, v166
	v_lshlrev_b32_e32 v188, 16, v167
	v_and_b32_e32 v167, 0xffff0000, v167
	v_fmac_f32_e32 v185, v126, v149
	v_fmac_f32_e32 v164, v127, v160
	v_fmac_f32_e32 v186, v128, v182
	v_fmac_f32_e32 v165, v129, v161
	v_fmac_f32_e32 v187, v122, v183
	v_fmac_f32_e32 v166, v123, v162
	v_fmac_f32_e32 v188, v124, v184
	v_fmac_f32_e32 v167, v125, v163
	v_cvt_pk_bf16_f32 v122, v185, v164
	v_cvt_pk_bf16_f32 v123, v186, v165
	v_cvt_pk_bf16_f32 v124, v187, v166
	v_cvt_pk_bf16_f32 v125, v188, v167
	global_store_dwordx4 v[178:179], v[122:125], off sc0 sc1
	global_load_dwordx4 v[122:125], v[176:177], off
	v_lshlrev_b32_e32 v149, 16, v168
	v_and_b32_e32 v162, 0xffff0000, v168
	v_lshlrev_b32_e32 v163, 16, v169
	v_and_b32_e32 v164, 0xffff0000, v169
	v_lshlrev_b32_e32 v165, 16, v170
	v_and_b32_e32 v166, 0xffff0000, v170
	v_lshlrev_b32_e32 v167, 16, v171
	v_and_b32_e32 v168, 0xffff0000, v171
	v_mul_f32_e32 v149, 0xbfb8aa3b, v149
	v_mul_f32_e32 v162, 0xbfb8aa3b, v162
	v_mul_f32_e32 v163, 0xbfb8aa3b, v163
	v_mul_f32_e32 v164, 0xbfb8aa3b, v164
	v_mul_f32_e32 v165, 0xbfb8aa3b, v165
	v_mul_f32_e32 v166, 0xbfb8aa3b, v166
	v_mul_f32_e32 v167, 0xbfb8aa3b, v167
	v_mul_f32_e32 v168, 0xbfb8aa3b, v168
	v_lshl_add_u64 v[160:161], v[180:181], 0, v[146:147]
	v_exp_f32_e32 v149, v149
	v_exp_f32_e32 v162, v162
	v_exp_f32_e32 v163, v163
	v_exp_f32_e32 v164, v164
	v_exp_f32_e32 v165, v165
	v_exp_f32_e32 v166, v166
	v_exp_f32_e32 v167, v167
	v_exp_f32_e32 v168, v168
	global_load_dwordx4 v[126:129], v[160:161], off
	v_add_f32_e32 v149, 1.0, v149
	v_add_f32_e32 v162, 1.0, v162
	v_add_f32_e32 v163, 1.0, v163
	v_add_f32_e32 v164, 1.0, v164
	v_add_f32_e32 v165, 1.0, v165
	v_add_f32_e32 v166, 1.0, v166
	v_add_f32_e32 v167, 1.0, v167
	v_add_f32_e32 v168, 1.0, v168
	v_rcp_f32_e32 v149, v149
	v_rcp_f32_e32 v162, v162
	v_rcp_f32_e32 v163, v163
	v_rcp_f32_e32 v164, v164
	v_rcp_f32_e32 v165, v165
	v_rcp_f32_e32 v166, v166
	v_rcp_f32_e32 v167, v167
	v_rcp_f32_e32 v168, v168
	v_lshlrev_b32_e32 v169, 16, v172
	v_and_b32_e32 v170, 0xffff0000, v172
	v_lshlrev_b32_e32 v171, 16, v173
	v_and_b32_e32 v172, 0xffff0000, v173
	v_lshlrev_b32_e32 v173, 16, v174
	v_and_b32_e32 v174, 0xffff0000, v174
	v_lshlrev_b32_e32 v180, 16, v175
	v_and_b32_e32 v175, 0xffff0000, v175
	v_fmac_f32_e32 v169, v118, v149
	v_fmac_f32_e32 v170, v119, v162
	v_fmac_f32_e32 v171, v120, v163
	v_fmac_f32_e32 v172, v121, v164
	v_fmac_f32_e32 v173, v114, v165
	v_fmac_f32_e32 v174, v115, v166
	v_fmac_f32_e32 v180, v116, v167
	v_fmac_f32_e32 v175, v117, v168
	v_cvt_pk_bf16_f32 v114, v169, v170
	v_cvt_pk_bf16_f32 v115, v171, v172
	v_cvt_pk_bf16_f32 v116, v173, v174
	v_cvt_pk_bf16_f32 v117, v180, v175
	global_store_dwordx4 v[178:179], v[114:117], off offset:256 sc0 sc1
	global_load_dwordx4 v[114:117], v[176:177], off offset:256
	s_waitcnt vmcnt(3)
	v_lshlrev_b32_e32 v118, 16, v122
	v_and_b32_e32 v119, 0xffff0000, v122
	v_lshlrev_b32_e32 v120, 16, v123
	v_and_b32_e32 v121, 0xffff0000, v123
	v_mul_f32_e32 v118, 0xbfb8aa3b, v118
	v_mul_f32_e32 v119, 0xbfb8aa3b, v119
	v_mul_f32_e32 v120, 0xbfb8aa3b, v120
	v_mul_f32_e32 v121, 0xbfb8aa3b, v121
	v_exp_f32_e32 v118, v118
	v_exp_f32_e32 v119, v119
	v_exp_f32_e32 v120, v120
	v_exp_f32_e32 v121, v121
	v_add_f32_e32 v118, 1.0, v118
	v_add_f32_e32 v119, 1.0, v119
	v_add_f32_e32 v120, 1.0, v120
	v_add_f32_e32 v121, 1.0, v121
	v_rcp_f32_e32 v149, v118
	v_rcp_f32_e32 v162, v119
	v_rcp_f32_e32 v163, v120
	v_rcp_f32_e32 v164, v121
	global_load_dwordx4 v[118:121], v[160:161], off offset:256
	v_lshlrev_b32_e32 v122, 16, v124
	v_and_b32_e32 v123, 0xffff0000, v124
	v_mul_f32_e32 v122, 0xbfb8aa3b, v122
	v_lshlrev_b32_e32 v124, 16, v125
	v_mul_f32_e32 v123, 0xbfb8aa3b, v123
	v_exp_f32_e32 v122, v122
	v_and_b32_e32 v125, 0xffff0000, v125
	v_mul_f32_e32 v124, 0xbfb8aa3b, v124
	v_exp_f32_e32 v123, v123
	v_mul_f32_e32 v125, 0xbfb8aa3b, v125
	v_exp_f32_e32 v124, v124
	v_exp_f32_e32 v125, v125
	v_add_f32_e32 v122, 1.0, v122
	s_waitcnt vmcnt(3)
	v_lshlrev_b32_e32 v160, 16, v126
	v_add_f32_e32 v123, 1.0, v123
	v_rcp_f32_e32 v122, v122
	v_fmac_f32_e32 v160, v110, v149
	v_and_b32_e32 v110, 0xffff0000, v126
	v_rcp_f32_e32 v123, v123
	v_add_f32_e32 v124, 1.0, v124
	v_fmac_f32_e32 v110, v111, v162
	v_lshlrev_b32_e32 v111, 16, v127
	v_rcp_f32_e32 v124, v124
	v_add_f32_e32 v125, 1.0, v125
	v_fmac_f32_e32 v111, v112, v163
	v_and_b32_e32 v112, 0xffff0000, v127
	v_rcp_f32_e32 v125, v125
	v_fmac_f32_e32 v112, v113, v164
	v_lshlrev_b32_e32 v113, 16, v128
	v_fmac_f32_e32 v113, v106, v122
	v_and_b32_e32 v122, 0xffff0000, v128
	v_fmac_f32_e32 v122, v107, v123
	v_lshlrev_b32_e32 v123, 16, v129
	v_fmac_f32_e32 v123, v108, v124
	v_and_b32_e32 v124, 0xffff0000, v129
	v_cvt_pk_bf16_f32 v106, v160, v110
	v_cvt_pk_bf16_f32 v107, v111, v112
	v_lshl_add_u64 v[110:111], s[2:3], 0, v[152:153]
	v_fmac_f32_e32 v124, v109, v125
	v_cvt_pk_bf16_f32 v108, v113, v122
	v_cvt_pk_bf16_f32 v109, v123, v124
	v_lshl_add_u64 v[122:123], v[110:111], 0, v[146:147]
	global_store_dwordx4 v[122:123], v[106:109], off sc0 sc1
	v_or_b32_e32 v110, 32, v148
	s_waitcnt vmcnt(2)
	v_and_b32_e32 v112, 0xffff0000, v114
	v_lshlrev_b32_e32 v106, 16, v114
	v_mul_f32_e32 v106, 0xbfb8aa3b, v106
	v_exp_f32_e32 v111, v106
	v_mad_i64_i32 v[106:107], s[24:25], v110, s45, v[150:151]
	v_lshl_add_u64 v[124:125], v[106:107], 0, v[146:147]
	v_mul_f32_e32 v112, 0xbfb8aa3b, v112
	global_load_dwordx4 v[106:109], v[124:125], off
	v_exp_f32_e32 v112, v112
	v_add_f32_e32 v111, 1.0, v111
	v_rcp_f32_e32 v126, v111
	v_and_b32_e32 v113, 0xffff0000, v115
	v_add_f32_e32 v111, 1.0, v112
	v_lshlrev_b32_e32 v112, 16, v115
	v_mul_f32_e32 v112, 0xbfb8aa3b, v112
	v_exp_f32_e32 v112, v112
	v_mul_f32_e32 v113, 0xbfb8aa3b, v113
	v_rcp_f32_e32 v127, v111
	v_exp_f32_e32 v113, v113
	v_add_f32_e32 v111, 1.0, v112
	v_lshlrev_b32_e32 v112, 16, v116
	v_mul_f32_e32 v112, 0xbfb8aa3b, v112
	v_exp_f32_e32 v112, v112
	v_rcp_f32_e32 v128, v111
	v_add_f32_e32 v111, 1.0, v113
	v_and_b32_e32 v113, 0xffff0000, v116
	v_mul_f32_e32 v113, 0xbfb8aa3b, v113
	v_rcp_f32_e32 v129, v111
	v_add_f32_e32 v111, 1.0, v112
	v_lshlrev_b32_e32 v112, 16, v117
	v_exp_f32_e32 v113, v113
	v_mul_f32_e32 v112, 0xbfb8aa3b, v112
	v_exp_f32_e32 v112, v112
	v_rcp_f32_e32 v149, v111
	v_add_f32_e32 v111, 1.0, v113
	v_and_b32_e32 v113, 0xffff0000, v117
	v_mul_f32_e32 v113, 0xbfb8aa3b, v113
	v_rcp_f32_e32 v152, v111
	v_add_f32_e32 v111, 1.0, v112
	v_exp_f32_e32 v113, v113
	v_rcp_f32_e32 v153, v111
	v_ashrrev_i32_e32 v111, 31, v110
	v_lshlrev_b64 v[114:115], 12, v[110:111]
	v_lshl_add_u64 v[110:111], s[6:7], 0, v[114:115]
	v_lshl_add_u64 v[116:117], v[110:111], 0, v[146:147]
	v_add_f32_e32 v160, 1.0, v113
	global_load_dwordx4 v[110:113], v[116:117], off
	s_waitcnt vmcnt(3)
	v_lshlrev_b32_e32 v161, 16, v118
	v_rcp_f32_e32 v160, v160
	v_fmac_f32_e32 v161, v102, v126
	v_and_b32_e32 v102, 0xffff0000, v118
	v_fmac_f32_e32 v102, v103, v127
	v_lshlrev_b32_e32 v103, 16, v119
	v_fmac_f32_e32 v103, v104, v128
	v_and_b32_e32 v104, 0xffff0000, v119
	v_fmac_f32_e32 v104, v105, v129
	v_lshlrev_b32_e32 v105, 16, v120
	v_and_b32_e32 v118, 0xffff0000, v120
	v_lshlrev_b32_e32 v119, 16, v121
	v_and_b32_e32 v120, 0xffff0000, v121
	v_fmac_f32_e32 v105, v98, v149
	v_fmac_f32_e32 v118, v99, v152
	v_fmac_f32_e32 v119, v100, v153
	v_fmac_f32_e32 v120, v101, v160
	v_cvt_pk_bf16_f32 v98, v161, v102
	v_cvt_pk_bf16_f32 v99, v103, v104
	v_cvt_pk_bf16_f32 v100, v105, v118
	v_cvt_pk_bf16_f32 v101, v119, v120
	global_store_dwordx4 v[122:123], v[98:101], off offset:256 sc0 sc1
	global_load_dwordx4 v[98:101], v[124:125], off offset:256
	s_waitcnt vmcnt(3)
	v_lshlrev_b32_e32 v102, 16, v106
	v_mul_f32_e32 v102, 0xbfb8aa3b, v102
	v_and_b32_e32 v103, 0xffff0000, v106
	v_exp_f32_e32 v102, v102
	v_mul_f32_e32 v103, 0xbfb8aa3b, v103
	v_exp_f32_e32 v103, v103
	v_and_b32_e32 v104, 0xffff0000, v107
	v_add_f32_e32 v102, 1.0, v102
	v_rcp_f32_e32 v106, v102
	v_add_f32_e32 v102, 1.0, v103
	v_lshlrev_b32_e32 v103, 16, v107
	v_mul_f32_e32 v103, 0xbfb8aa3b, v103
	v_exp_f32_e32 v103, v103
	v_mul_f32_e32 v104, 0xbfb8aa3b, v104
	v_rcp_f32_e32 v107, v102
	v_exp_f32_e32 v104, v104
	v_add_f32_e32 v102, 1.0, v103
	v_lshlrev_b32_e32 v103, 16, v108
	v_mul_f32_e32 v103, 0xbfb8aa3b, v103
	v_exp_f32_e32 v103, v103
	v_rcp_f32_e32 v118, v102
	v_add_f32_e32 v102, 1.0, v104
	v_and_b32_e32 v104, 0xffff0000, v108
	v_mul_f32_e32 v104, 0xbfb8aa3b, v104
	v_rcp_f32_e32 v108, v102
	v_add_f32_e32 v102, 1.0, v103
	v_exp_f32_e32 v104, v104
	v_rcp_f32_e32 v119, v102
	v_lshlrev_b32_e32 v102, 16, v109
	v_mul_f32_e32 v102, 0xbfb8aa3b, v102
	v_exp_f32_e32 v121, v102
	v_and_b32_e32 v102, 0xffff0000, v109
	v_mul_f32_e32 v102, 0xbfb8aa3b, v102
	v_add_f32_e32 v120, 1.0, v104
	v_exp_f32_e32 v109, v102
	global_load_dwordx4 v[102:105], v[116:117], off offset:256
	v_rcp_f32_e32 v116, v120
	v_add_f32_e32 v117, 1.0, v121
	v_rcp_f32_e32 v117, v117
	s_waitcnt vmcnt(3)
	v_lshlrev_b32_e32 v120, 16, v110
	v_add_f32_e32 v109, 1.0, v109
	v_fmac_f32_e32 v120, v94, v106
	v_and_b32_e32 v94, 0xffff0000, v110
	v_rcp_f32_e32 v109, v109
	v_fmac_f32_e32 v94, v95, v107
	v_lshlrev_b32_e32 v95, 16, v111
	v_fmac_f32_e32 v95, v96, v118
	v_and_b32_e32 v96, 0xffff0000, v111
	v_fmac_f32_e32 v96, v97, v108
	v_lshlrev_b32_e32 v97, 16, v112
	v_and_b32_e32 v106, 0xffff0000, v112
	v_lshlrev_b32_e32 v107, 16, v113
	v_fmac_f32_e32 v97, v90, v119
	v_fmac_f32_e32 v106, v91, v116
	v_fmac_f32_e32 v107, v92, v117
	v_and_b32_e32 v108, 0xffff0000, v113
	v_cvt_pk_bf16_f32 v90, v120, v94
	v_cvt_pk_bf16_f32 v91, v95, v96
	v_lshl_add_u64 v[94:95], s[2:3], 0, v[114:115]
	v_fmac_f32_e32 v108, v93, v109
	v_cvt_pk_bf16_f32 v92, v97, v106
	v_cvt_pk_bf16_f32 v93, v107, v108
	v_lshl_add_u64 v[106:107], v[94:95], 0, v[146:147]
	global_store_dwordx4 v[106:107], v[90:93], off sc0 sc1
	v_or_b32_e32 v94, 48, v148
	s_waitcnt vmcnt(2)
	v_and_b32_e32 v96, 0xffff0000, v98
	v_lshlrev_b32_e32 v90, 16, v98
	v_mul_f32_e32 v90, 0xbfb8aa3b, v90
	v_exp_f32_e32 v95, v90
	v_mad_i64_i32 v[90:91], s[24:25], v94, s45, v[150:151]
	v_lshl_add_u64 v[108:109], v[90:91], 0, v[146:147]
	global_load_dwordx4 v[90:93], v[108:109], off
	v_mul_f32_e32 v96, 0xbfb8aa3b, v96
	v_exp_f32_e32 v96, v96
	v_add_f32_e32 v95, 1.0, v95
	v_rcp_f32_e32 v110, v95
	v_and_b32_e32 v97, 0xffff0000, v99
	v_add_f32_e32 v95, 1.0, v96
	v_lshlrev_b32_e32 v96, 16, v99
	v_mul_f32_e32 v96, 0xbfb8aa3b, v96
	v_exp_f32_e32 v96, v96
	v_mul_f32_e32 v97, 0xbfb8aa3b, v97
	v_rcp_f32_e32 v111, v95
	v_exp_f32_e32 v97, v97
	v_add_f32_e32 v95, 1.0, v96
	v_lshlrev_b32_e32 v96, 16, v100
	v_mul_f32_e32 v96, 0xbfb8aa3b, v96
	v_exp_f32_e32 v96, v96
	v_rcp_f32_e32 v112, v95
	v_add_f32_e32 v95, 1.0, v97
	v_and_b32_e32 v97, 0xffff0000, v100
	v_mul_f32_e32 v97, 0xbfb8aa3b, v97
	v_rcp_f32_e32 v113, v95
	v_add_f32_e32 v95, 1.0, v96
	v_lshlrev_b32_e32 v96, 16, v101
	v_exp_f32_e32 v97, v97
	v_mul_f32_e32 v96, 0xbfb8aa3b, v96
	v_exp_f32_e32 v96, v96
	v_rcp_f32_e32 v114, v95
	v_add_f32_e32 v95, 1.0, v97
	v_and_b32_e32 v97, 0xffff0000, v101
	v_mul_f32_e32 v97, 0xbfb8aa3b, v97
	v_rcp_f32_e32 v115, v95
	v_add_f32_e32 v95, 1.0, v96
	v_exp_f32_e32 v97, v97
	v_rcp_f32_e32 v116, v95
	v_ashrrev_i32_e32 v95, 31, v94
	v_lshlrev_b64 v[98:99], 12, v[94:95]
	v_lshl_add_u64 v[94:95], s[6:7], 0, v[98:99]
	v_lshl_add_u64 v[100:101], v[94:95], 0, v[146:147]
	v_add_f32_e32 v117, 1.0, v97
	global_load_dwordx4 v[94:97], v[100:101], off
	v_rcp_f32_e32 v117, v117
	s_waitcnt vmcnt(3)
	v_lshlrev_b32_e32 v118, 16, v102
	v_fmac_f32_e32 v118, v86, v110
	v_and_b32_e32 v86, 0xffff0000, v102
	v_fmac_f32_e32 v86, v87, v111
	v_lshlrev_b32_e32 v87, 16, v103
	v_fmac_f32_e32 v87, v88, v112
	v_and_b32_e32 v88, 0xffff0000, v103
	v_fmac_f32_e32 v88, v89, v113
	v_lshlrev_b32_e32 v89, 16, v104
	v_and_b32_e32 v102, 0xffff0000, v104
	v_lshlrev_b32_e32 v103, 16, v105
	v_and_b32_e32 v104, 0xffff0000, v105
	v_fmac_f32_e32 v89, v82, v114
	v_fmac_f32_e32 v102, v83, v115
	v_fmac_f32_e32 v103, v84, v116
	v_fmac_f32_e32 v104, v85, v117
	v_cvt_pk_bf16_f32 v82, v118, v86
	v_cvt_pk_bf16_f32 v83, v87, v88
	v_cvt_pk_bf16_f32 v84, v89, v102
	v_cvt_pk_bf16_f32 v85, v103, v104
	global_store_dwordx4 v[106:107], v[82:85], off offset:256 sc0 sc1
	global_load_dwordx4 v[82:85], v[108:109], off offset:256
	s_waitcnt vmcnt(3)
	v_lshlrev_b32_e32 v86, 16, v90
	v_mul_f32_e32 v86, 0xbfb8aa3b, v86
	v_and_b32_e32 v87, 0xffff0000, v90
	v_exp_f32_e32 v86, v86
	v_mul_f32_e32 v87, 0xbfb8aa3b, v87
	v_exp_f32_e32 v87, v87
	v_and_b32_e32 v88, 0xffff0000, v91
	v_add_f32_e32 v86, 1.0, v86
	v_rcp_f32_e32 v90, v86
	v_add_f32_e32 v86, 1.0, v87
	v_lshlrev_b32_e32 v87, 16, v91
	v_mul_f32_e32 v87, 0xbfb8aa3b, v87
	v_exp_f32_e32 v87, v87
	v_mul_f32_e32 v88, 0xbfb8aa3b, v88
	v_rcp_f32_e32 v91, v86
	v_exp_f32_e32 v88, v88
	v_add_f32_e32 v86, 1.0, v87
	v_lshlrev_b32_e32 v87, 16, v92
	v_mul_f32_e32 v87, 0xbfb8aa3b, v87
	v_exp_f32_e32 v87, v87
	v_rcp_f32_e32 v102, v86
	v_add_f32_e32 v86, 1.0, v88
	v_and_b32_e32 v88, 0xffff0000, v92
	v_mul_f32_e32 v88, 0xbfb8aa3b, v88
	v_rcp_f32_e32 v92, v86
	v_add_f32_e32 v86, 1.0, v87
	v_exp_f32_e32 v88, v88
	v_rcp_f32_e32 v103, v86
	v_lshlrev_b32_e32 v86, 16, v93
	v_mul_f32_e32 v86, 0xbfb8aa3b, v86
	v_exp_f32_e32 v105, v86
	v_and_b32_e32 v86, 0xffff0000, v93
	v_mul_f32_e32 v86, 0xbfb8aa3b, v86
	v_add_f32_e32 v104, 1.0, v88
	v_exp_f32_e32 v93, v86
	global_load_dwordx4 v[86:89], v[100:101], off offset:256
	v_rcp_f32_e32 v100, v104
	v_add_f32_e32 v101, 1.0, v105
	v_rcp_f32_e32 v101, v101
	v_add_f32_e32 v93, 1.0, v93
	s_waitcnt vmcnt(3)
	v_lshlrev_b32_e32 v104, 16, v94
	v_fmac_f32_e32 v104, v78, v90
	v_and_b32_e32 v78, 0xffff0000, v94
	v_rcp_f32_e32 v93, v93
	v_fmac_f32_e32 v78, v79, v91
	v_lshlrev_b32_e32 v79, 16, v95
	v_fmac_f32_e32 v79, v80, v102
	v_and_b32_e32 v80, 0xffff0000, v95
	v_fmac_f32_e32 v80, v81, v92
	v_lshlrev_b32_e32 v81, 16, v96
	v_and_b32_e32 v90, 0xffff0000, v96
	v_lshlrev_b32_e32 v91, 16, v97
	v_fmac_f32_e32 v81, v74, v103
	v_fmac_f32_e32 v90, v75, v100
	v_fmac_f32_e32 v91, v76, v101
	v_and_b32_e32 v92, 0xffff0000, v97
	v_cvt_pk_bf16_f32 v74, v104, v78
	v_cvt_pk_bf16_f32 v75, v79, v80
	v_lshl_add_u64 v[78:79], s[2:3], 0, v[98:99]
	v_fmac_f32_e32 v92, v77, v93
	v_cvt_pk_bf16_f32 v76, v81, v90
	v_cvt_pk_bf16_f32 v77, v91, v92
	v_lshl_add_u64 v[90:91], v[78:79], 0, v[146:147]
	global_store_dwordx4 v[90:91], v[74:77], off sc0 sc1
	v_add_u32_e32 v78, 0x80, v148
	s_waitcnt vmcnt(2)
	v_and_b32_e32 v80, 0xffff0000, v82
	v_lshlrev_b32_e32 v74, 16, v82
	v_mul_f32_e32 v74, 0xbfb8aa3b, v74
	v_exp_f32_e32 v79, v74
	v_mad_i64_i32 v[74:75], s[24:25], v78, s45, v[150:151]
	v_lshl_add_u64 v[92:93], v[74:75], 0, v[146:147]
	v_mul_f32_e32 v80, 0xbfb8aa3b, v80
	global_load_dwordx4 v[74:77], v[92:93], off
	v_exp_f32_e32 v80, v80
	v_add_f32_e32 v79, 1.0, v79
	v_rcp_f32_e32 v94, v79
	v_and_b32_e32 v81, 0xffff0000, v83
	v_add_f32_e32 v79, 1.0, v80
	v_lshlrev_b32_e32 v80, 16, v83
	v_mul_f32_e32 v80, 0xbfb8aa3b, v80
	v_exp_f32_e32 v80, v80
	v_mul_f32_e32 v81, 0xbfb8aa3b, v81
	v_rcp_f32_e32 v95, v79
	v_exp_f32_e32 v81, v81
	v_add_f32_e32 v79, 1.0, v80
	v_lshlrev_b32_e32 v80, 16, v84
	v_mul_f32_e32 v80, 0xbfb8aa3b, v80
	v_exp_f32_e32 v80, v80
	v_rcp_f32_e32 v96, v79
	v_add_f32_e32 v79, 1.0, v81
	v_and_b32_e32 v81, 0xffff0000, v84
	v_mul_f32_e32 v81, 0xbfb8aa3b, v81
	v_rcp_f32_e32 v97, v79
	v_add_f32_e32 v79, 1.0, v80
	v_lshlrev_b32_e32 v80, 16, v85
	v_exp_f32_e32 v81, v81
	v_mul_f32_e32 v80, 0xbfb8aa3b, v80
	v_exp_f32_e32 v80, v80
	v_rcp_f32_e32 v98, v79
	v_add_f32_e32 v79, 1.0, v81
	v_and_b32_e32 v81, 0xffff0000, v85
	v_mul_f32_e32 v81, 0xbfb8aa3b, v81
	v_rcp_f32_e32 v99, v79
	v_add_f32_e32 v79, 1.0, v80
	v_exp_f32_e32 v81, v81
	v_rcp_f32_e32 v100, v79
	v_ashrrev_i32_e32 v79, 31, v78
	v_lshlrev_b64 v[82:83], 12, v[78:79]
	v_lshl_add_u64 v[78:79], s[6:7], 0, v[82:83]
	v_lshl_add_u64 v[84:85], v[78:79], 0, v[146:147]
	v_add_f32_e32 v101, 1.0, v81
	global_load_dwordx4 v[78:81], v[84:85], off
	v_rcp_f32_e32 v101, v101
	s_waitcnt vmcnt(3)
	v_lshlrev_b32_e32 v102, 16, v86
	v_fmac_f32_e32 v102, v70, v94
	v_and_b32_e32 v70, 0xffff0000, v86
	v_fmac_f32_e32 v70, v71, v95
	v_lshlrev_b32_e32 v71, 16, v87
	v_fmac_f32_e32 v71, v72, v96
	v_and_b32_e32 v72, 0xffff0000, v87
	v_fmac_f32_e32 v72, v73, v97
	v_lshlrev_b32_e32 v73, 16, v88
	v_and_b32_e32 v86, 0xffff0000, v88
	v_lshlrev_b32_e32 v87, 16, v89
	v_and_b32_e32 v88, 0xffff0000, v89
	v_fmac_f32_e32 v73, v66, v98
	v_fmac_f32_e32 v86, v67, v99
	v_fmac_f32_e32 v87, v68, v100
	v_fmac_f32_e32 v88, v69, v101
	v_cvt_pk_bf16_f32 v66, v102, v70
	v_cvt_pk_bf16_f32 v67, v71, v72
	v_cvt_pk_bf16_f32 v68, v73, v86
	v_cvt_pk_bf16_f32 v69, v87, v88
	global_store_dwordx4 v[90:91], v[66:69], off offset:256 sc0 sc1
	global_load_dwordx4 v[66:69], v[92:93], off offset:256
	s_waitcnt vmcnt(3)
	v_lshlrev_b32_e32 v70, 16, v74
	v_mul_f32_e32 v70, 0xbfb8aa3b, v70
	v_and_b32_e32 v71, 0xffff0000, v74
	v_exp_f32_e32 v70, v70
	v_mul_f32_e32 v71, 0xbfb8aa3b, v71
	v_exp_f32_e32 v71, v71
	v_and_b32_e32 v72, 0xffff0000, v75
	v_add_f32_e32 v70, 1.0, v70
	v_rcp_f32_e32 v74, v70
	v_add_f32_e32 v70, 1.0, v71
	v_lshlrev_b32_e32 v71, 16, v75
	v_mul_f32_e32 v71, 0xbfb8aa3b, v71
	v_exp_f32_e32 v71, v71
	v_mul_f32_e32 v72, 0xbfb8aa3b, v72
	v_rcp_f32_e32 v75, v70
	v_exp_f32_e32 v72, v72
	v_add_f32_e32 v70, 1.0, v71
	v_lshlrev_b32_e32 v71, 16, v76
	v_mul_f32_e32 v71, 0xbfb8aa3b, v71
	v_exp_f32_e32 v71, v71
	v_rcp_f32_e32 v86, v70
	v_add_f32_e32 v70, 1.0, v72
	v_and_b32_e32 v72, 0xffff0000, v76
	v_mul_f32_e32 v72, 0xbfb8aa3b, v72
	v_rcp_f32_e32 v76, v70
	v_add_f32_e32 v70, 1.0, v71
	v_exp_f32_e32 v72, v72
	v_rcp_f32_e32 v87, v70
	v_lshlrev_b32_e32 v70, 16, v77
	v_mul_f32_e32 v70, 0xbfb8aa3b, v70
	v_exp_f32_e32 v89, v70
	v_and_b32_e32 v70, 0xffff0000, v77
	v_mul_f32_e32 v70, 0xbfb8aa3b, v70
	v_add_f32_e32 v88, 1.0, v72
	v_exp_f32_e32 v77, v70
	global_load_dwordx4 v[70:73], v[84:85], off offset:256
	v_rcp_f32_e32 v84, v88
	v_add_f32_e32 v85, 1.0, v89
	v_rcp_f32_e32 v85, v85
	s_waitcnt vmcnt(3)
	v_lshlrev_b32_e32 v88, 16, v78
	v_add_f32_e32 v77, 1.0, v77
	v_fmac_f32_e32 v88, v62, v74
	v_and_b32_e32 v62, 0xffff0000, v78
	v_rcp_f32_e32 v77, v77
	v_fmac_f32_e32 v62, v63, v75
	v_lshlrev_b32_e32 v63, 16, v79
	v_fmac_f32_e32 v63, v64, v86
	v_and_b32_e32 v64, 0xffff0000, v79
	v_fmac_f32_e32 v64, v65, v76
	v_lshlrev_b32_e32 v65, 16, v80
	v_and_b32_e32 v74, 0xffff0000, v80
	v_lshlrev_b32_e32 v75, 16, v81
	v_fmac_f32_e32 v65, v58, v87
	v_fmac_f32_e32 v74, v59, v84
	v_fmac_f32_e32 v75, v60, v85
	v_and_b32_e32 v76, 0xffff0000, v81
	v_cvt_pk_bf16_f32 v58, v88, v62
	v_cvt_pk_bf16_f32 v59, v63, v64
	v_lshl_add_u64 v[62:63], s[2:3], 0, v[82:83]
	v_fmac_f32_e32 v76, v61, v77
	v_cvt_pk_bf16_f32 v60, v65, v74
	v_cvt_pk_bf16_f32 v61, v75, v76
	v_lshl_add_u64 v[74:75], v[62:63], 0, v[146:147]
	global_store_dwordx4 v[74:75], v[58:61], off sc0 sc1
	v_add_u32_e32 v62, 0x90, v148
	s_waitcnt vmcnt(2)
	v_and_b32_e32 v64, 0xffff0000, v66
	v_lshlrev_b32_e32 v58, 16, v66
	v_mul_f32_e32 v58, 0xbfb8aa3b, v58
	v_exp_f32_e32 v63, v58
	v_mad_i64_i32 v[58:59], s[24:25], v62, s45, v[150:151]
	v_lshl_add_u64 v[76:77], v[58:59], 0, v[146:147]
	global_load_dwordx4 v[58:61], v[76:77], off
	v_mul_f32_e32 v64, 0xbfb8aa3b, v64
	v_exp_f32_e32 v64, v64
	v_add_f32_e32 v63, 1.0, v63
	v_rcp_f32_e32 v78, v63
	v_and_b32_e32 v65, 0xffff0000, v67
	v_add_f32_e32 v63, 1.0, v64
	v_lshlrev_b32_e32 v64, 16, v67
	v_mul_f32_e32 v64, 0xbfb8aa3b, v64
	v_exp_f32_e32 v64, v64
	v_mul_f32_e32 v65, 0xbfb8aa3b, v65
	v_rcp_f32_e32 v79, v63
	v_exp_f32_e32 v65, v65
	v_add_f32_e32 v63, 1.0, v64
	v_lshlrev_b32_e32 v64, 16, v68
	v_mul_f32_e32 v64, 0xbfb8aa3b, v64
	v_exp_f32_e32 v64, v64
	v_rcp_f32_e32 v80, v63
	v_add_f32_e32 v63, 1.0, v65
	v_and_b32_e32 v65, 0xffff0000, v68
	v_mul_f32_e32 v65, 0xbfb8aa3b, v65
	v_rcp_f32_e32 v81, v63
	v_add_f32_e32 v63, 1.0, v64
	v_lshlrev_b32_e32 v64, 16, v69
	v_exp_f32_e32 v65, v65
	v_mul_f32_e32 v64, 0xbfb8aa3b, v64
	v_exp_f32_e32 v64, v64
	v_rcp_f32_e32 v82, v63
	v_add_f32_e32 v63, 1.0, v65
	v_and_b32_e32 v65, 0xffff0000, v69
	v_mul_f32_e32 v65, 0xbfb8aa3b, v65
	v_rcp_f32_e32 v83, v63
	v_add_f32_e32 v63, 1.0, v64
	v_exp_f32_e32 v65, v65
	v_rcp_f32_e32 v84, v63
	v_ashrrev_i32_e32 v63, 31, v62
	v_lshlrev_b64 v[66:67], 12, v[62:63]
	v_lshl_add_u64 v[62:63], s[6:7], 0, v[66:67]
	v_lshl_add_u64 v[68:69], v[62:63], 0, v[146:147]
	v_add_f32_e32 v85, 1.0, v65
	global_load_dwordx4 v[62:65], v[68:69], off
	v_rcp_f32_e32 v85, v85
	s_waitcnt vmcnt(3)
	v_lshlrev_b32_e32 v86, 16, v70
	v_fmac_f32_e32 v86, v54, v78
	v_and_b32_e32 v54, 0xffff0000, v70
	v_fmac_f32_e32 v54, v55, v79
	v_lshlrev_b32_e32 v55, 16, v71
	v_fmac_f32_e32 v55, v56, v80
	v_and_b32_e32 v56, 0xffff0000, v71
	v_fmac_f32_e32 v56, v57, v81
	v_lshlrev_b32_e32 v57, 16, v72
	v_and_b32_e32 v70, 0xffff0000, v72
	v_lshlrev_b32_e32 v71, 16, v73
	v_and_b32_e32 v72, 0xffff0000, v73
	v_fmac_f32_e32 v57, v50, v82
	v_fmac_f32_e32 v70, v51, v83
	v_fmac_f32_e32 v71, v52, v84
	v_fmac_f32_e32 v72, v53, v85
	v_cvt_pk_bf16_f32 v50, v86, v54
	v_cvt_pk_bf16_f32 v51, v55, v56
	v_cvt_pk_bf16_f32 v52, v57, v70
	v_cvt_pk_bf16_f32 v53, v71, v72
	global_store_dwordx4 v[74:75], v[50:53], off offset:256 sc0 sc1
	global_load_dwordx4 v[50:53], v[76:77], off offset:256
	s_waitcnt vmcnt(3)
	v_lshlrev_b32_e32 v54, 16, v58
	v_mul_f32_e32 v54, 0xbfb8aa3b, v54
	v_and_b32_e32 v55, 0xffff0000, v58
	v_exp_f32_e32 v54, v54
	v_mul_f32_e32 v55, 0xbfb8aa3b, v55
	v_exp_f32_e32 v55, v55
	v_and_b32_e32 v56, 0xffff0000, v59
	v_add_f32_e32 v54, 1.0, v54
	v_rcp_f32_e32 v58, v54
	v_add_f32_e32 v54, 1.0, v55
	v_lshlrev_b32_e32 v55, 16, v59
	v_mul_f32_e32 v55, 0xbfb8aa3b, v55
	v_exp_f32_e32 v55, v55
	v_mul_f32_e32 v56, 0xbfb8aa3b, v56
	v_rcp_f32_e32 v59, v54
	v_exp_f32_e32 v56, v56
	v_add_f32_e32 v54, 1.0, v55
	v_lshlrev_b32_e32 v55, 16, v60
	v_mul_f32_e32 v55, 0xbfb8aa3b, v55
	v_exp_f32_e32 v55, v55
	v_rcp_f32_e32 v70, v54
	v_add_f32_e32 v54, 1.0, v56
	v_and_b32_e32 v56, 0xffff0000, v60
	v_mul_f32_e32 v56, 0xbfb8aa3b, v56
	v_rcp_f32_e32 v60, v54
	v_add_f32_e32 v54, 1.0, v55
	v_exp_f32_e32 v56, v56
	v_rcp_f32_e32 v71, v54
	v_lshlrev_b32_e32 v54, 16, v61
	v_mul_f32_e32 v54, 0xbfb8aa3b, v54
	v_exp_f32_e32 v73, v54
	v_and_b32_e32 v54, 0xffff0000, v61
	v_mul_f32_e32 v54, 0xbfb8aa3b, v54
	v_add_f32_e32 v72, 1.0, v56
	v_exp_f32_e32 v61, v54
	global_load_dwordx4 v[54:57], v[68:69], off offset:256
	v_rcp_f32_e32 v68, v72
	v_add_f32_e32 v69, 1.0, v73
	v_rcp_f32_e32 v69, v69
	v_add_f32_e32 v61, 1.0, v61
	s_waitcnt vmcnt(3)
	v_lshlrev_b32_e32 v72, 16, v62
	v_fmac_f32_e32 v72, v46, v58
	v_and_b32_e32 v46, 0xffff0000, v62
	v_rcp_f32_e32 v61, v61
	v_fmac_f32_e32 v46, v47, v59
	v_lshlrev_b32_e32 v47, 16, v63
	v_fmac_f32_e32 v47, v48, v70
	v_and_b32_e32 v48, 0xffff0000, v63
	v_fmac_f32_e32 v48, v49, v60
	v_lshlrev_b32_e32 v49, 16, v64
	v_and_b32_e32 v58, 0xffff0000, v64
	v_lshlrev_b32_e32 v59, 16, v65
	v_fmac_f32_e32 v49, v42, v71
	v_fmac_f32_e32 v58, v43, v68
	v_fmac_f32_e32 v59, v44, v69
	v_and_b32_e32 v60, 0xffff0000, v65
	v_cvt_pk_bf16_f32 v42, v72, v46
	v_cvt_pk_bf16_f32 v43, v47, v48
	v_lshl_add_u64 v[46:47], s[2:3], 0, v[66:67]
	v_fmac_f32_e32 v60, v45, v61
	v_cvt_pk_bf16_f32 v44, v49, v58
	v_cvt_pk_bf16_f32 v45, v59, v60
	v_lshl_add_u64 v[58:59], v[46:47], 0, v[146:147]
	global_store_dwordx4 v[58:59], v[42:45], off sc0 sc1
	v_add_u32_e32 v46, 0xa0, v148
	s_waitcnt vmcnt(2)
	v_and_b32_e32 v48, 0xffff0000, v50
	v_lshlrev_b32_e32 v42, 16, v50
	v_mul_f32_e32 v42, 0xbfb8aa3b, v42
	v_exp_f32_e32 v47, v42
	v_mad_i64_i32 v[42:43], s[24:25], v46, s45, v[150:151]
	v_lshl_add_u64 v[60:61], v[42:43], 0, v[146:147]
	v_mul_f32_e32 v48, 0xbfb8aa3b, v48
	global_load_dwordx4 v[42:45], v[60:61], off
	v_exp_f32_e32 v48, v48
	v_add_f32_e32 v47, 1.0, v47
	v_rcp_f32_e32 v62, v47
	v_and_b32_e32 v49, 0xffff0000, v51
	v_add_f32_e32 v47, 1.0, v48
	v_lshlrev_b32_e32 v48, 16, v51
	v_mul_f32_e32 v48, 0xbfb8aa3b, v48
	v_exp_f32_e32 v48, v48
	v_mul_f32_e32 v49, 0xbfb8aa3b, v49
	v_rcp_f32_e32 v63, v47
	v_exp_f32_e32 v49, v49
	v_add_f32_e32 v47, 1.0, v48
	v_lshlrev_b32_e32 v48, 16, v52
	v_mul_f32_e32 v48, 0xbfb8aa3b, v48
	v_exp_f32_e32 v48, v48
	v_rcp_f32_e32 v64, v47
	v_add_f32_e32 v47, 1.0, v49
	v_and_b32_e32 v49, 0xffff0000, v52
	v_mul_f32_e32 v49, 0xbfb8aa3b, v49
	v_rcp_f32_e32 v65, v47
	v_add_f32_e32 v47, 1.0, v48
	v_lshlrev_b32_e32 v48, 16, v53
	v_exp_f32_e32 v49, v49
	v_mul_f32_e32 v48, 0xbfb8aa3b, v48
	v_exp_f32_e32 v48, v48
	v_rcp_f32_e32 v66, v47
	v_add_f32_e32 v47, 1.0, v49
	v_and_b32_e32 v49, 0xffff0000, v53
	v_mul_f32_e32 v49, 0xbfb8aa3b, v49
	v_rcp_f32_e32 v67, v47
	v_add_f32_e32 v47, 1.0, v48
	v_exp_f32_e32 v49, v49
	v_rcp_f32_e32 v68, v47
	v_ashrrev_i32_e32 v47, 31, v46
	v_lshlrev_b64 v[50:51], 12, v[46:47]
	v_lshl_add_u64 v[46:47], s[6:7], 0, v[50:51]
	v_lshl_add_u64 v[52:53], v[46:47], 0, v[146:147]
	v_add_f32_e32 v69, 1.0, v49
	global_load_dwordx4 v[46:49], v[52:53], off
	v_rcp_f32_e32 v69, v69
	s_waitcnt vmcnt(3)
	v_lshlrev_b32_e32 v70, 16, v54
	v_fmac_f32_e32 v70, v38, v62
	v_and_b32_e32 v38, 0xffff0000, v54
	v_fmac_f32_e32 v38, v39, v63
	v_lshlrev_b32_e32 v39, 16, v55
	v_fmac_f32_e32 v39, v40, v64
	v_and_b32_e32 v40, 0xffff0000, v55
	v_fmac_f32_e32 v40, v41, v65
	v_lshlrev_b32_e32 v41, 16, v56
	v_and_b32_e32 v54, 0xffff0000, v56
	v_lshlrev_b32_e32 v55, 16, v57
	v_and_b32_e32 v56, 0xffff0000, v57
	v_fmac_f32_e32 v41, v34, v66
	v_fmac_f32_e32 v54, v35, v67
	v_fmac_f32_e32 v55, v36, v68
	v_fmac_f32_e32 v56, v37, v69
	v_cvt_pk_bf16_f32 v34, v70, v38
	v_cvt_pk_bf16_f32 v35, v39, v40
	v_cvt_pk_bf16_f32 v36, v41, v54
	v_cvt_pk_bf16_f32 v37, v55, v56
	global_store_dwordx4 v[58:59], v[34:37], off offset:256 sc0 sc1
	global_load_dwordx4 v[34:37], v[60:61], off offset:256
	s_waitcnt vmcnt(3)
	v_lshlrev_b32_e32 v38, 16, v42
	v_mul_f32_e32 v38, 0xbfb8aa3b, v38
	v_and_b32_e32 v39, 0xffff0000, v42
	v_exp_f32_e32 v38, v38
	v_mul_f32_e32 v39, 0xbfb8aa3b, v39
	v_exp_f32_e32 v39, v39
	v_and_b32_e32 v40, 0xffff0000, v43
	v_add_f32_e32 v38, 1.0, v38
	v_rcp_f32_e32 v42, v38
	v_add_f32_e32 v38, 1.0, v39
	v_lshlrev_b32_e32 v39, 16, v43
	v_mul_f32_e32 v39, 0xbfb8aa3b, v39
	v_exp_f32_e32 v39, v39
	v_mul_f32_e32 v40, 0xbfb8aa3b, v40
	v_rcp_f32_e32 v43, v38
	v_exp_f32_e32 v40, v40
	v_add_f32_e32 v38, 1.0, v39
	v_lshlrev_b32_e32 v39, 16, v44
	v_mul_f32_e32 v39, 0xbfb8aa3b, v39
	v_exp_f32_e32 v39, v39
	v_rcp_f32_e32 v54, v38
	v_add_f32_e32 v38, 1.0, v40
	v_and_b32_e32 v40, 0xffff0000, v44
	v_rcp_f32_e32 v44, v38
	v_add_f32_e32 v38, 1.0, v39
	v_rcp_f32_e32 v55, v38
	v_lshlrev_b32_e32 v38, 16, v45
	v_mul_f32_e32 v40, 0xbfb8aa3b, v40
	v_mul_f32_e32 v38, 0xbfb8aa3b, v38
	v_exp_f32_e32 v40, v40
	v_exp_f32_e32 v57, v38
	v_and_b32_e32 v38, 0xffff0000, v45
	v_mul_f32_e32 v38, 0xbfb8aa3b, v38
	v_exp_f32_e32 v45, v38
	v_add_f32_e32 v56, 1.0, v40
	global_load_dwordx4 v[38:41], v[52:53], off offset:256
	v_rcp_f32_e32 v52, v56
	v_add_f32_e32 v53, 1.0, v57
	v_rcp_f32_e32 v53, v53
	s_waitcnt vmcnt(3)
	v_lshlrev_b32_e32 v56, 16, v46
	v_add_f32_e32 v45, 1.0, v45
	v_fmac_f32_e32 v56, v30, v42
	v_and_b32_e32 v30, 0xffff0000, v46
	v_rcp_f32_e32 v45, v45
	v_fmac_f32_e32 v30, v31, v43
	v_lshlrev_b32_e32 v31, 16, v47
	v_fmac_f32_e32 v31, v32, v54
	v_and_b32_e32 v32, 0xffff0000, v47
	v_fmac_f32_e32 v32, v33, v44
	v_lshlrev_b32_e32 v33, 16, v48
	v_and_b32_e32 v42, 0xffff0000, v48
	v_lshlrev_b32_e32 v43, 16, v49
	v_fmac_f32_e32 v33, v26, v55
	v_fmac_f32_e32 v42, v27, v52
	v_fmac_f32_e32 v43, v28, v53
	v_and_b32_e32 v44, 0xffff0000, v49
	v_cvt_pk_bf16_f32 v26, v56, v30
	v_cvt_pk_bf16_f32 v27, v31, v32
	v_lshl_add_u64 v[30:31], s[2:3], 0, v[50:51]
	v_fmac_f32_e32 v44, v29, v45
	v_cvt_pk_bf16_f32 v28, v33, v42
	v_cvt_pk_bf16_f32 v29, v43, v44
	v_lshl_add_u64 v[42:43], v[30:31], 0, v[146:147]
	global_store_dwordx4 v[42:43], v[26:29], off sc0 sc1
	v_add_u32_e32 v30, 0xb0, v148
	s_waitcnt vmcnt(2)
	v_and_b32_e32 v32, 0xffff0000, v34
	v_lshlrev_b32_e32 v26, 16, v34
	v_mul_f32_e32 v26, 0xbfb8aa3b, v26
	v_exp_f32_e32 v31, v26
	v_mad_i64_i32 v[26:27], s[24:25], v30, s45, v[150:151]
	v_lshl_add_u64 v[44:45], v[26:27], 0, v[146:147]
	global_load_dwordx4 v[26:29], v[44:45], off
	v_mul_f32_e32 v32, 0xbfb8aa3b, v32
	v_exp_f32_e32 v32, v32
	v_add_f32_e32 v31, 1.0, v31
	v_rcp_f32_e32 v46, v31
	v_and_b32_e32 v33, 0xffff0000, v35
	v_add_f32_e32 v31, 1.0, v32
	v_lshlrev_b32_e32 v32, 16, v35
	v_mul_f32_e32 v32, 0xbfb8aa3b, v32
	v_exp_f32_e32 v32, v32
	v_mul_f32_e32 v33, 0xbfb8aa3b, v33
	v_exp_f32_e32 v33, v33
	v_rcp_f32_e32 v47, v31
	v_add_f32_e32 v31, 1.0, v32
	v_lshlrev_b32_e32 v32, 16, v36
	v_rcp_f32_e32 v48, v31
	v_add_f32_e32 v31, 1.0, v33
	v_mul_f32_e32 v32, 0xbfb8aa3b, v32
	v_and_b32_e32 v33, 0xffff0000, v36
	v_exp_f32_e32 v32, v32
	v_mul_f32_e32 v33, 0xbfb8aa3b, v33
	v_exp_f32_e32 v33, v33
	v_rcp_f32_e32 v49, v31
	v_add_f32_e32 v31, 1.0, v32
	v_lshlrev_b32_e32 v32, 16, v37
	v_rcp_f32_e32 v50, v31
	v_add_f32_e32 v31, 1.0, v33
	v_mul_f32_e32 v32, 0xbfb8aa3b, v32
	v_and_b32_e32 v33, 0xffff0000, v37
	v_exp_f32_e32 v32, v32
	v_mul_f32_e32 v33, 0xbfb8aa3b, v33
	v_exp_f32_e32 v33, v33
	v_rcp_f32_e32 v51, v31
	v_add_f32_e32 v31, 1.0, v32
	v_rcp_f32_e32 v52, v31
	v_add_f32_e32 v31, 1.0, v33
	v_rcp_f32_e32 v53, v31
	v_ashrrev_i32_e32 v31, 31, v30
	v_lshlrev_b64 v[34:35], 12, v[30:31]
	v_lshl_add_u64 v[30:31], s[6:7], 0, v[34:35]
	v_lshl_add_u64 v[36:37], v[30:31], 0, v[146:147]
	global_load_dwordx4 v[30:33], v[36:37], off
	s_waitcnt vmcnt(3)
	v_lshlrev_b32_e32 v54, 16, v38
	v_fmac_f32_e32 v54, v22, v46
	v_and_b32_e32 v22, 0xffff0000, v38
	v_fmac_f32_e32 v22, v23, v47
	v_lshlrev_b32_e32 v23, 16, v39
	v_fmac_f32_e32 v23, v24, v48
	v_and_b32_e32 v24, 0xffff0000, v39
	v_fmac_f32_e32 v24, v25, v49
	v_lshlrev_b32_e32 v25, 16, v40
	v_and_b32_e32 v38, 0xffff0000, v40
	v_lshlrev_b32_e32 v39, 16, v41
	v_and_b32_e32 v40, 0xffff0000, v41
	v_fmac_f32_e32 v25, v18, v50
	v_fmac_f32_e32 v38, v19, v51
	v_fmac_f32_e32 v39, v20, v52
	v_fmac_f32_e32 v40, v21, v53
	v_cvt_pk_bf16_f32 v18, v54, v22
	v_cvt_pk_bf16_f32 v19, v23, v24
	v_cvt_pk_bf16_f32 v20, v25, v38
	v_cvt_pk_bf16_f32 v21, v39, v40
	global_store_dwordx4 v[42:43], v[18:21], off offset:256 sc0 sc1
	global_load_dwordx4 v[18:21], v[44:45], off offset:256
	s_waitcnt vmcnt(3)
	v_lshlrev_b32_e32 v22, 16, v26
	v_mul_f32_e32 v22, 0xbfb8aa3b, v22
	v_and_b32_e32 v23, 0xffff0000, v26
	v_exp_f32_e32 v22, v22
	v_mul_f32_e32 v23, 0xbfb8aa3b, v23
	v_exp_f32_e32 v23, v23
	v_and_b32_e32 v24, 0xffff0000, v27
	v_add_f32_e32 v22, 1.0, v22
	v_rcp_f32_e32 v26, v22
	v_add_f32_e32 v22, 1.0, v23
	v_lshlrev_b32_e32 v23, 16, v27
	v_mul_f32_e32 v23, 0xbfb8aa3b, v23
	v_exp_f32_e32 v23, v23
	v_mul_f32_e32 v24, 0xbfb8aa3b, v24
	v_exp_f32_e32 v24, v24
	v_rcp_f32_e32 v27, v22
	v_add_f32_e32 v22, 1.0, v23
	v_rcp_f32_e32 v38, v22
	v_lshlrev_b32_e32 v22, 16, v28
	v_mul_f32_e32 v22, 0xbfb8aa3b, v22
	v_exp_f32_e32 v40, v22
	v_and_b32_e32 v22, 0xffff0000, v28
	v_add_f32_e32 v39, 1.0, v24
	v_mul_f32_e32 v28, 0xbfb8aa3b, v22
	global_load_dwordx4 v[22:25], v[36:37], off offset:256
	v_rcp_f32_e32 v36, v39
	v_lshlrev_b32_e32 v39, 16, v29
	v_mul_f32_e32 v39, 0xbfb8aa3b, v39
	v_exp_f32_e32 v28, v28
	v_exp_f32_e32 v39, v39
	v_and_b32_e32 v29, 0xffff0000, v29
	v_add_f32_e32 v37, 1.0, v40
	v_mul_f32_e32 v29, 0xbfb8aa3b, v29
	v_rcp_f32_e32 v37, v37
	v_add_f32_e32 v28, 1.0, v28
	v_exp_f32_e32 v29, v29
	v_add_f32_e32 v39, 1.0, v39
	v_rcp_f32_e32 v28, v28
	v_rcp_f32_e32 v39, v39
	v_add_f32_e32 v29, 1.0, v29
	v_rcp_f32_e32 v29, v29
	s_waitcnt vmcnt(3)
	v_lshlrev_b32_e32 v40, 16, v30
	v_fmac_f32_e32 v40, v14, v26
	v_and_b32_e32 v14, 0xffff0000, v30
	v_fmac_f32_e32 v14, v15, v27
	v_lshlrev_b32_e32 v15, 16, v31
	v_fmac_f32_e32 v15, v16, v38
	v_and_b32_e32 v16, 0xffff0000, v31
	v_fmac_f32_e32 v16, v17, v36
	v_lshlrev_b32_e32 v17, 16, v32
	v_fmac_f32_e32 v17, v10, v37
	v_and_b32_e32 v26, 0xffff0000, v32
	v_lshlrev_b32_e32 v27, 16, v33
	v_fmac_f32_e32 v26, v11, v28
	v_fmac_f32_e32 v27, v12, v39
	v_cvt_pk_bf16_f32 v11, v15, v16
	v_cvt_pk_bf16_f32 v12, v17, v26
	v_cvt_pk_bf16_f32 v10, v40, v14
	v_lshl_add_u64 v[14:15], s[2:3], 0, v[34:35]
	v_and_b32_e32 v28, 0xffff0000, v33
	v_lshl_add_u64 v[14:15], v[14:15], 0, v[146:147]
	v_fmac_f32_e32 v28, v13, v29
	v_cvt_pk_bf16_f32 v13, v27, v28
	global_store_dwordx4 v[14:15], v[10:13], off sc0 sc1
	s_waitcnt vmcnt(2)
	v_lshlrev_b32_e32 v16, 16, v18
	v_and_b32_e32 v17, 0xffff0000, v18
	v_mul_f32_e32 v16, 0xbfb8aa3b, v16
	v_mul_f32_e32 v17, 0xbfb8aa3b, v17
	v_exp_f32_e32 v16, v16
	v_exp_f32_e32 v17, v17
	v_lshlrev_b32_e32 v12, 16, v19
	v_mul_f32_e32 v12, 0xbfb8aa3b, v12
	v_and_b32_e32 v13, 0xffff0000, v19
	v_add_f32_e32 v10, 1.0, v16
	v_add_f32_e32 v11, 1.0, v17
	v_exp_f32_e32 v12, v12
	v_mul_f32_e32 v13, 0xbfb8aa3b, v13
	v_lshlrev_b32_e32 v16, 16, v20
	v_and_b32_e32 v17, 0xffff0000, v20
	v_lshlrev_b32_e32 v18, 16, v21
	v_and_b32_e32 v19, 0xffff0000, v21
	v_exp_f32_e32 v13, v13
	v_mul_f32_e32 v16, 0xbfb8aa3b, v16
	v_mul_f32_e32 v17, 0xbfb8aa3b, v17
	v_mul_f32_e32 v18, 0xbfb8aa3b, v18
	v_mul_f32_e32 v19, 0xbfb8aa3b, v19
	v_exp_f32_e32 v16, v16
	v_exp_f32_e32 v17, v17
	v_exp_f32_e32 v18, v18
	v_exp_f32_e32 v19, v19
	v_rcp_f32_e32 v10, v10
	v_rcp_f32_e32 v11, v11
	v_add_f32_e32 v12, 1.0, v12
	v_rcp_f32_e32 v12, v12
	v_add_f32_e32 v13, 1.0, v13
	v_rcp_f32_e32 v13, v13
	v_add_f32_e32 v16, 1.0, v16
	v_add_f32_e32 v17, 1.0, v17
	v_add_f32_e32 v18, 1.0, v18
	v_add_f32_e32 v19, 1.0, v19
	v_rcp_f32_e32 v16, v16
	v_rcp_f32_e32 v17, v17
	v_rcp_f32_e32 v18, v18
	v_rcp_f32_e32 v19, v19
	s_waitcnt vmcnt(1)
	v_lshlrev_b32_e32 v20, 16, v22
	v_fmac_f32_e32 v20, v6, v10
	v_and_b32_e32 v6, 0xffff0000, v22
	v_fmac_f32_e32 v6, v7, v11
	v_lshlrev_b32_e32 v7, 16, v23
	v_fmac_f32_e32 v7, v8, v12
	v_and_b32_e32 v8, 0xffff0000, v23
	v_fmac_f32_e32 v8, v9, v13
	v_lshlrev_b32_e32 v9, 16, v24
	v_and_b32_e32 v10, 0xffff0000, v24
	v_lshlrev_b32_e32 v11, 16, v25
	v_and_b32_e32 v12, 0xffff0000, v25
	v_fmac_f32_e32 v9, v2, v16
	v_fmac_f32_e32 v10, v3, v17
	v_fmac_f32_e32 v11, v4, v18
	v_fmac_f32_e32 v12, v5, v19
	v_cvt_pk_bf16_f32 v2, v20, v6
	v_cvt_pk_bf16_f32 v3, v7, v8
	v_cvt_pk_bf16_f32 v4, v9, v10
	v_cvt_pk_bf16_f32 v5, v11, v12
	global_store_dwordx4 v[14:15], v[2:5], off offset:256 sc0 sc1
	s_cbranch_vccnz .LBB0_907
	s_andn2_b64 vcc, exec, s[0:1]
	s_cbranch_vccnz .LBB0_906
	s_barrier
	s_branch .LBB0_906

.LBB0_1012:
	v_lshl_add_u32 v146, s26, 8, v1
	v_lshl_or_b32 v148, s60, 8, v151
	v_ashrrev_i32_e32 v147, 31, v146
	v_cvt_pk_bf16_f32 v126, v126, v127
	v_cvt_pk_bf16_f32 v127, v128, v129
	v_cvt_pk_bf16_f32 v128, v122, v123
	v_lshlrev_b64 v[122:123], 12, v[146:147]
	v_ashrrev_i32_e32 v149, 31, v148
	v_cvt_pk_bf16_f32 v129, v124, v125
	v_lshl_add_u64 v[122:123], s[6:7], 0, v[122:123]
	v_lshlrev_b64 v[124:125], 1, v[148:149]
	v_lshl_add_u64 v[122:123], v[122:123], 0, v[124:125]
	v_cvt_pk_bf16_f32 v114, v114, v115
	v_cvt_pk_bf16_f32 v115, v116, v117
	v_cvt_pk_bf16_f32 v116, v106, v107
	v_cvt_pk_bf16_f32 v117, v108, v109
	global_store_dwordx4 v[122:123], v[114:117], off offset:256 sc0 sc1
	v_cvt_pk_bf16_f32 v108, v110, v111
	v_cvt_pk_bf16_f32 v98, v98, v99
	v_cvt_pk_bf16_f32 v99, v100, v101
	v_cvt_pk_bf16_f32 v100, v90, v91
	v_cvt_pk_bf16_f32 v101, v92, v93
	s_nop 1
	v_or_b32_e32 v114, 16, v146
	v_ashrrev_i32_e32 v115, 31, v114
	v_lshlrev_b64 v[110:111], 12, v[114:115]
	v_lshl_add_u64 v[110:111], s[6:7], 0, v[110:111]
	v_lshl_add_u64 v[110:111], v[110:111], 0, v[124:125]
	global_store_dwordx4 v[110:111], v[98:101], off offset:256 sc0 sc1
	v_cvt_pk_bf16_f32 v62, v62, v63
	v_cvt_pk_bf16_f32 v63, v64, v65
	v_cvt_pk_bf16_f32 v65, v60, v61
	v_add_co_u32_e32 v60, vcc, s55, v122
	s_nop 0
	v_or_b32_e32 v98, 32, v146
	v_ashrrev_i32_e32 v99, 31, v98
	v_cvt_pk_bf16_f32 v92, v94, v95
	v_lshlrev_b64 v[94:95], 12, v[98:99]
	v_addc_co_u32_e32 v61, vcc, 0, v123, vcc
	v_lshl_add_u64 v[94:95], s[6:7], 0, v[94:95]
	v_cvt_pk_bf16_f32 v50, v50, v51
	v_cvt_pk_bf16_f32 v51, v52, v53
	v_cvt_pk_bf16_f32 v53, v44, v45
	v_cvt_pk_bf16_f32 v45, v48, v49
	v_add_co_u32_e32 v48, vcc, s56, v122
	v_lshl_add_u64 v[94:95], v[94:95], 0, v[124:125]
	v_cvt_pk_bf16_f32 v82, v82, v83
	s_nop 0
	v_addc_co_u32_e32 v49, vcc, 0, v123, vcc
	v_cvt_pk_bf16_f32 v83, v84, v85
	v_cvt_pk_bf16_f32 v84, v74, v75
	v_cvt_pk_bf16_f32 v85, v76, v77
	global_store_dwordx4 v[94:95], v[82:85], off offset:256 sc0 sc1
	v_cvt_pk_bf16_f32 v34, v34, v35
	v_cvt_pk_bf16_f32 v35, v36, v37
	v_cvt_pk_bf16_f32 v37, v28, v29
	v_cvt_pk_bf16_f32 v29, v32, v33
	v_add_co_u32_e32 v32, vcc, s57, v122
	s_nop 0
	v_or_b32_e32 v82, 48, v146
	v_ashrrev_i32_e32 v83, 31, v82
	v_addc_co_u32_e32 v33, vcc, 0, v123, vcc
	v_cvt_pk_bf16_f32 v76, v78, v79
	v_lshlrev_b64 v[78:79], 12, v[82:83]
	v_cvt_pk_bf16_f32 v18, v18, v19
	v_cvt_pk_bf16_f32 v19, v20, v21
	v_cvt_pk_bf16_f32 v21, v12, v13
	v_cvt_pk_bf16_f32 v13, v16, v17
	v_add_co_u32_e32 v16, vcc, s58, v122
	v_lshl_add_u64 v[78:79], s[6:7], 0, v[78:79]
	s_nop 0
	v_addc_co_u32_e32 v17, vcc, 0, v123, vcc
	v_lshl_add_u64 v[78:79], v[78:79], 0, v[124:125]
	v_cvt_pk_bf16_f32 v64, v58, v59
	v_lshl_add_u64 v[58:59], v[122:123], 0, s[0:1]
	v_cvt_pk_bf16_f32 v44, v46, v47
	v_lshl_add_u64 v[46:47], v[122:123], 0, s[12:13]
	v_cvt_pk_bf16_f32 v28, v30, v31
	v_lshl_add_u64 v[30:31], v[122:123], 0, s[14:15]
	v_cvt_pk_bf16_f32 v12, v14, v15
	v_lshl_add_u64 v[14:15], v[122:123], 0, s[16:17]
	s_andn2_b64 vcc, exec, s[4:5]
	s_mov_b64 s[4:5], -1
	global_store_dwordx4 v[122:123], v[126:129], off sc0 sc1
	v_cvt_pk_bf16_f32 v106, v118, v119
	v_cvt_pk_bf16_f32 v107, v120, v121
	v_cvt_pk_bf16_f32 v109, v112, v113
	global_store_dwordx4 v[110:111], v[106:109], off sc0 sc1
	v_cvt_pk_bf16_f32 v90, v102, v103
	v_cvt_pk_bf16_f32 v91, v104, v105
	v_cvt_pk_bf16_f32 v93, v96, v97
	global_store_dwordx4 v[94:95], v[90:93], off sc0 sc1
	v_cvt_pk_bf16_f32 v74, v86, v87
	v_cvt_pk_bf16_f32 v75, v88, v89
	v_cvt_pk_bf16_f32 v77, v80, v81
	global_store_dwordx4 v[78:79], v[74:77], off sc0 sc1
	v_cvt_pk_bf16_f32 v70, v70, v71
	v_cvt_pk_bf16_f32 v71, v72, v73
	v_cvt_pk_bf16_f32 v72, v66, v67
	v_cvt_pk_bf16_f32 v73, v68, v69
	global_store_dwordx4 v[78:79], v[70:73], off offset:256 sc0 sc1
	global_store_dwordx4 v[60:61], v[62:65], off sc0 sc1
	v_cvt_pk_bf16_f32 v52, v42, v43
	global_store_dwordx4 v[58:59], v[50:53], off offset:256 sc0 sc1
	v_cvt_pk_bf16_f32 v42, v54, v55
	v_cvt_pk_bf16_f32 v43, v56, v57
	global_store_dwordx4 v[48:49], v[42:45], off sc0 sc1
	v_cvt_pk_bf16_f32 v36, v26, v27
	global_store_dwordx4 v[46:47], v[34:37], off offset:256 sc0 sc1
	v_cvt_pk_bf16_f32 v26, v38, v39
	v_cvt_pk_bf16_f32 v27, v40, v41
	global_store_dwordx4 v[32:33], v[26:29], off sc0 sc1
	v_cvt_pk_bf16_f32 v20, v10, v11
	global_store_dwordx4 v[30:31], v[18:21], off offset:256 sc0 sc1
	v_cvt_pk_bf16_f32 v10, v22, v23
	v_cvt_pk_bf16_f32 v11, v24, v25
	global_store_dwordx4 v[16:17], v[10:13], off sc0 sc1
	v_cvt_pk_bf16_f32 v6, v6, v7
	v_cvt_pk_bf16_f32 v7, v8, v9
	v_cvt_pk_bf16_f32 v8, v2, v3
	v_cvt_pk_bf16_f32 v9, v4, v5
	global_store_dwordx4 v[14:15], v[6:9], off offset:256 sc0 sc1
	s_cbranch_vccnz .LBB0_1001
	s_andn2_b64 vcc, exec, s[2:3]
	s_cbranch_vccnz .LBB0_1000
	s_barrier
	s_branch .LBB0_1000

.LBB0_1176:
	v_lshl_add_u32 v156, s18, 8, v1
	v_lshl_or_b32 v146, s50, 8, v151
	v_cvt_pk_bf16_f32 v126, v126, v127
	v_cvt_pk_bf16_f32 v127, v128, v129
	v_cvt_pk_bf16_f32 v128, v122, v123
	v_mov_b64_e32 v[122:123], s[2:3]
	v_ashrrev_i32_e32 v147, 31, v146
	v_cvt_pk_bf16_f32 v70, v70, v71
	v_cvt_pk_bf16_f32 v71, v72, v73
	v_cvt_pk_bf16_f32 v72, v66, v67
	v_add_u32_e32 v66, 0x80, v156
	v_cvt_pk_bf16_f32 v129, v124, v125
	v_mad_i64_i32 v[148:149], s[20:21], v156, s48, v[122:123]
	v_lshlrev_b64 v[124:125], 1, v[146:147]
	v_cvt_pk_bf16_f32 v62, v62, v63
	v_cvt_pk_bf16_f32 v63, v64, v65
	v_cvt_pk_bf16_f32 v64, v58, v59
	v_mad_i64_i32 v[58:59], s[20:21], v66, s48, v[122:123]
	v_lshl_add_u64 v[146:147], v[148:149], 0, v[124:125]
	v_cvt_pk_bf16_f32 v114, v114, v115
	v_lshl_add_u64 v[58:59], v[58:59], 0, v[124:125]
	v_cvt_pk_bf16_f32 v50, v50, v51
	v_cvt_pk_bf16_f32 v115, v116, v117
	v_cvt_pk_bf16_f32 v116, v106, v107
	v_cvt_pk_bf16_f32 v117, v108, v109
	global_store_dwordx4 v[146:147], v[114:117], off offset:256 sc0 sc1
	v_cvt_pk_bf16_f32 v51, v52, v53
	v_cvt_pk_bf16_f32 v52, v42, v43
	v_cvt_pk_bf16_f32 v53, v44, v45
	global_store_dwordx4 v[58:59], v[50:53], off offset:256 sc0 sc1
	v_cvt_pk_bf16_f32 v108, v110, v111
	s_nop 0
	v_or_b32_e32 v114, 16, v156
	v_mad_i64_i32 v[110:111], s[20:21], v114, s48, v[122:123]
	v_add_u32_e32 v50, 0x90, v156
	v_cvt_pk_bf16_f32 v44, v46, v47
	v_mad_i64_i32 v[46:47], s[20:21], v50, s48, v[122:123]
	v_lshl_add_u64 v[110:111], v[110:111], 0, v[124:125]
	v_cvt_pk_bf16_f32 v98, v98, v99
	v_lshl_add_u64 v[46:47], v[46:47], 0, v[124:125]
	v_cvt_pk_bf16_f32 v34, v34, v35
	v_cvt_pk_bf16_f32 v99, v100, v101
	v_cvt_pk_bf16_f32 v100, v90, v91
	v_cvt_pk_bf16_f32 v101, v92, v93
	global_store_dwordx4 v[110:111], v[98:101], off offset:256 sc0 sc1
	v_cvt_pk_bf16_f32 v35, v36, v37
	v_cvt_pk_bf16_f32 v36, v26, v27
	v_cvt_pk_bf16_f32 v37, v28, v29
	global_store_dwordx4 v[46:47], v[34:37], off offset:256 sc0 sc1
	v_cvt_pk_bf16_f32 v92, v94, v95
	s_nop 0
	v_or_b32_e32 v98, 32, v156
	v_mad_i64_i32 v[94:95], s[20:21], v98, s48, v[122:123]
	v_add_u32_e32 v34, 0xa0, v156
	v_cvt_pk_bf16_f32 v28, v30, v31
	v_mad_i64_i32 v[30:31], s[20:21], v34, s48, v[122:123]
	v_lshl_add_u64 v[94:95], v[94:95], 0, v[124:125]
	v_cvt_pk_bf16_f32 v82, v82, v83
	v_lshl_add_u64 v[30:31], v[30:31], 0, v[124:125]
	v_cvt_pk_bf16_f32 v18, v18, v19
	v_cvt_pk_bf16_f32 v83, v84, v85
	v_cvt_pk_bf16_f32 v84, v74, v75
	v_cvt_pk_bf16_f32 v85, v76, v77
	global_store_dwordx4 v[94:95], v[82:85], off offset:256 sc0 sc1
	v_cvt_pk_bf16_f32 v19, v20, v21
	v_cvt_pk_bf16_f32 v20, v10, v11
	v_cvt_pk_bf16_f32 v21, v12, v13
	global_store_dwordx4 v[30:31], v[18:21], off offset:256 sc0 sc1
	v_cvt_pk_bf16_f32 v76, v78, v79
	s_nop 0
	v_or_b32_e32 v82, 48, v156
	v_mad_i64_i32 v[78:79], s[20:21], v82, s48, v[122:123]
	v_add_u32_e32 v18, 0xb0, v156
	v_cvt_pk_bf16_f32 v12, v14, v15
	v_mad_i64_i32 v[14:15], s[20:21], v18, s48, v[122:123]
	v_lshl_add_u64 v[78:79], v[78:79], 0, v[124:125]
	v_lshl_add_u64 v[14:15], v[14:15], 0, v[124:125]
	s_andn2_b64 vcc, exec, s[4:5]
	s_mov_b64 s[4:5], -1
	global_store_dwordx4 v[146:147], v[126:129], off sc0 sc1
	v_cvt_pk_bf16_f32 v106, v118, v119
	v_cvt_pk_bf16_f32 v107, v120, v121
	v_cvt_pk_bf16_f32 v109, v112, v113
	global_store_dwordx4 v[110:111], v[106:109], off sc0 sc1
	v_cvt_pk_bf16_f32 v90, v102, v103
	v_cvt_pk_bf16_f32 v91, v104, v105
	v_cvt_pk_bf16_f32 v93, v96, v97
	global_store_dwordx4 v[94:95], v[90:93], off sc0 sc1
	v_cvt_pk_bf16_f32 v74, v86, v87
	v_cvt_pk_bf16_f32 v75, v88, v89
	v_cvt_pk_bf16_f32 v77, v80, v81
	global_store_dwordx4 v[78:79], v[74:77], off sc0 sc1
	v_cvt_pk_bf16_f32 v73, v68, v69
	global_store_dwordx4 v[78:79], v[70:73], off offset:256 sc0 sc1
	v_cvt_pk_bf16_f32 v65, v60, v61
	global_store_dwordx4 v[58:59], v[62:65], off sc0 sc1
	v_cvt_pk_bf16_f32 v42, v54, v55
	v_cvt_pk_bf16_f32 v43, v56, v57
	v_cvt_pk_bf16_f32 v45, v48, v49
	global_store_dwordx4 v[46:47], v[42:45], off sc0 sc1
	v_cvt_pk_bf16_f32 v26, v38, v39
	v_cvt_pk_bf16_f32 v27, v40, v41
	v_cvt_pk_bf16_f32 v29, v32, v33
	global_store_dwordx4 v[30:31], v[26:29], off sc0 sc1
	v_cvt_pk_bf16_f32 v10, v22, v23
	v_cvt_pk_bf16_f32 v11, v24, v25
	v_cvt_pk_bf16_f32 v13, v16, v17
	global_store_dwordx4 v[14:15], v[10:13], off sc0 sc1
	v_cvt_pk_bf16_f32 v6, v6, v7
	v_cvt_pk_bf16_f32 v7, v8, v9
	v_cvt_pk_bf16_f32 v8, v2, v3
	v_cvt_pk_bf16_f32 v9, v4, v5
	global_store_dwordx4 v[14:15], v[6:9], off offset:256 sc0 sc1
	s_cbranch_vccnz .LBB0_1169
	s_andn2_b64 vcc, exec, s[0:1]
	s_cbranch_vccnz .LBB0_1168
	s_barrier
	s_branch .LBB0_1168

.LBB0_1420:
	v_lshl_add_u32 v146, s57, 8, v1
	v_lshl_or_b32 v148, s58, 8, v151
	v_ashrrev_i32_e32 v147, 31, v146
	v_cvt_pk_bf16_f32 v126, v126, v127
	v_cvt_pk_bf16_f32 v127, v128, v129
	v_cvt_pk_bf16_f32 v128, v122, v123
	v_lshlrev_b64 v[122:123], 12, v[146:147]
	v_ashrrev_i32_e32 v149, 31, v148
	v_cvt_pk_bf16_f32 v129, v124, v125
	v_lshl_add_u64 v[122:123], s[2:3], 0, v[122:123]
	v_lshlrev_b64 v[124:125], 1, v[148:149]
	v_lshl_add_u64 v[122:123], v[122:123], 0, v[124:125]
	v_cvt_pk_bf16_f32 v114, v114, v115
	v_cvt_pk_bf16_f32 v115, v116, v117
	v_cvt_pk_bf16_f32 v116, v106, v107
	v_cvt_pk_bf16_f32 v117, v108, v109
	global_store_dwordx4 v[122:123], v[114:117], off offset:256 sc0 sc1
	v_cvt_pk_bf16_f32 v108, v110, v111
	v_cvt_pk_bf16_f32 v98, v98, v99
	v_cvt_pk_bf16_f32 v99, v100, v101
	v_cvt_pk_bf16_f32 v100, v90, v91
	v_cvt_pk_bf16_f32 v101, v92, v93
	s_nop 1
	v_or_b32_e32 v114, 16, v146
	v_ashrrev_i32_e32 v115, 31, v114
	v_lshlrev_b64 v[110:111], 12, v[114:115]
	v_lshl_add_u64 v[110:111], s[2:3], 0, v[110:111]
	v_lshl_add_u64 v[110:111], v[110:111], 0, v[124:125]
	global_store_dwordx4 v[110:111], v[98:101], off offset:256 sc0 sc1
	v_cvt_pk_bf16_f32 v62, v62, v63
	v_cvt_pk_bf16_f32 v63, v64, v65
	v_cvt_pk_bf16_f32 v65, v60, v61
	v_add_co_u32_e32 v60, vcc, s50, v122
	s_nop 0
	v_or_b32_e32 v98, 32, v146
	v_ashrrev_i32_e32 v99, 31, v98
	v_cvt_pk_bf16_f32 v92, v94, v95
	v_lshlrev_b64 v[94:95], 12, v[98:99]
	v_addc_co_u32_e32 v61, vcc, 0, v123, vcc
	v_lshl_add_u64 v[94:95], s[2:3], 0, v[94:95]
	v_cvt_pk_bf16_f32 v50, v50, v51
	v_cvt_pk_bf16_f32 v51, v52, v53
	v_cvt_pk_bf16_f32 v53, v44, v45
	v_cvt_pk_bf16_f32 v45, v48, v49
	v_add_co_u32_e32 v48, vcc, s51, v122
	v_lshl_add_u64 v[94:95], v[94:95], 0, v[124:125]
	v_cvt_pk_bf16_f32 v82, v82, v83
	s_nop 0
	v_addc_co_u32_e32 v49, vcc, 0, v123, vcc
	v_cvt_pk_bf16_f32 v83, v84, v85
	v_cvt_pk_bf16_f32 v84, v74, v75
	v_cvt_pk_bf16_f32 v85, v76, v77
	global_store_dwordx4 v[94:95], v[82:85], off offset:256 sc0 sc1
	v_cvt_pk_bf16_f32 v34, v34, v35
	v_cvt_pk_bf16_f32 v35, v36, v37
	v_cvt_pk_bf16_f32 v37, v28, v29
	v_cvt_pk_bf16_f32 v29, v32, v33
	v_add_co_u32_e32 v32, vcc, s52, v122
	s_nop 0
	v_or_b32_e32 v82, 48, v146
	v_ashrrev_i32_e32 v83, 31, v82
	v_addc_co_u32_e32 v33, vcc, 0, v123, vcc
	v_cvt_pk_bf16_f32 v76, v78, v79
	v_lshlrev_b64 v[78:79], 12, v[82:83]
	v_cvt_pk_bf16_f32 v18, v18, v19
	v_cvt_pk_bf16_f32 v19, v20, v21
	v_cvt_pk_bf16_f32 v21, v12, v13
	v_cvt_pk_bf16_f32 v13, v16, v17
	v_add_co_u32_e32 v16, vcc, s53, v122
	v_lshl_add_u64 v[78:79], s[2:3], 0, v[78:79]
	s_nop 0
	v_addc_co_u32_e32 v17, vcc, 0, v123, vcc
	v_lshl_add_u64 v[78:79], v[78:79], 0, v[124:125]
	v_cvt_pk_bf16_f32 v64, v58, v59
	v_lshl_add_u64 v[58:59], v[122:123], 0, s[12:13]
	v_cvt_pk_bf16_f32 v44, v46, v47
	v_lshl_add_u64 v[46:47], v[122:123], 0, s[14:15]
	v_cvt_pk_bf16_f32 v28, v30, v31
	v_lshl_add_u64 v[30:31], v[122:123], 0, s[16:17]
	v_cvt_pk_bf16_f32 v12, v14, v15
	v_lshl_add_u64 v[14:15], v[122:123], 0, s[18:19]
	s_and_b64 vcc, exec, s[4:5]
	s_mov_b64 s[4:5], -1
	global_store_dwordx4 v[122:123], v[126:129], off sc0 sc1
	v_cvt_pk_bf16_f32 v106, v118, v119
	v_cvt_pk_bf16_f32 v107, v120, v121
	v_cvt_pk_bf16_f32 v109, v112, v113
	global_store_dwordx4 v[110:111], v[106:109], off sc0 sc1
	v_cvt_pk_bf16_f32 v90, v102, v103
	v_cvt_pk_bf16_f32 v91, v104, v105
	v_cvt_pk_bf16_f32 v93, v96, v97
	global_store_dwordx4 v[94:95], v[90:93], off sc0 sc1
	v_cvt_pk_bf16_f32 v74, v86, v87
	v_cvt_pk_bf16_f32 v75, v88, v89
	v_cvt_pk_bf16_f32 v77, v80, v81
	global_store_dwordx4 v[78:79], v[74:77], off sc0 sc1
	v_cvt_pk_bf16_f32 v70, v70, v71
	v_cvt_pk_bf16_f32 v71, v72, v73
	v_cvt_pk_bf16_f32 v72, v66, v67
	v_cvt_pk_bf16_f32 v73, v68, v69
	global_store_dwordx4 v[78:79], v[70:73], off offset:256 sc0 sc1
	global_store_dwordx4 v[60:61], v[62:65], off sc0 sc1
	v_cvt_pk_bf16_f32 v52, v42, v43
	global_store_dwordx4 v[58:59], v[50:53], off offset:256 sc0 sc1
	v_cvt_pk_bf16_f32 v42, v54, v55
	v_cvt_pk_bf16_f32 v43, v56, v57
	global_store_dwordx4 v[48:49], v[42:45], off sc0 sc1
	v_cvt_pk_bf16_f32 v36, v26, v27
	global_store_dwordx4 v[46:47], v[34:37], off offset:256 sc0 sc1
	v_cvt_pk_bf16_f32 v26, v38, v39
	v_cvt_pk_bf16_f32 v27, v40, v41
	global_store_dwordx4 v[32:33], v[26:29], off sc0 sc1
	v_cvt_pk_bf16_f32 v20, v10, v11
	global_store_dwordx4 v[30:31], v[18:21], off offset:256 sc0 sc1
	v_cvt_pk_bf16_f32 v10, v22, v23
	v_cvt_pk_bf16_f32 v11, v24, v25
	global_store_dwordx4 v[16:17], v[10:13], off sc0 sc1
	v_cvt_pk_bf16_f32 v6, v6, v7
	v_cvt_pk_bf16_f32 v7, v8, v9
	v_cvt_pk_bf16_f32 v8, v2, v3
	v_cvt_pk_bf16_f32 v9, v4, v5
	global_store_dwordx4 v[14:15], v[6:9], off offset:256 sc0 sc1
	s_cbranch_vccnz .LBB0_1405
	s_andn2_b64 vcc, exec, s[0:1]
	s_cbranch_vccnz .LBB0_1404
	s_barrier
	s_branch .LBB0_1404

.LBB0_1593:
	v_lshl_or_b32 v148, s68, 8, v152
	v_lshl_add_u32 v157, s67, 8, v1
	v_mov_b64_e32 v[146:147], s[8:9]
	v_ashrrev_i32_e32 v149, 31, v148
	v_mad_i64_i32 v[162:163], s[30:31], v157, s55, v[146:147]
	v_lshlrev_b64 v[148:149], 1, v[148:149]
	v_cvt_pk_bf16_f32 v158, v126, v127
	v_cvt_pk_bf16_f32 v159, v128, v129
	v_cvt_pk_bf16_f32 v160, v122, v123
	v_cvt_pk_bf16_f32 v161, v124, v125
	v_lshl_add_u64 v[162:163], v[162:163], 0, v[148:149]
	global_store_dwordx4 v[162:163], v[158:161], off sc0 sc1
	s_nop 1
	v_cvt_pk_bf16_f32 v158, v114, v115
	v_cvt_pk_bf16_f32 v159, v116, v117
	v_cvt_pk_bf16_f32 v160, v106, v107
	v_cvt_pk_bf16_f32 v161, v108, v109
	global_store_dwordx4 v[162:163], v[158:161], off offset:256 sc0 sc1
	v_or_b32_e32 v162, 16, v157
	v_mad_i64_i32 v[162:163], s[30:31], v162, s55, v[146:147]
	v_cvt_pk_bf16_f32 v158, v118, v119
	v_cvt_pk_bf16_f32 v159, v120, v121
	v_cvt_pk_bf16_f32 v160, v110, v111
	v_cvt_pk_bf16_f32 v161, v112, v113
	v_lshl_add_u64 v[162:163], v[162:163], 0, v[148:149]
	global_store_dwordx4 v[162:163], v[158:161], off sc0 sc1
	s_nop 1
	v_cvt_pk_bf16_f32 v158, v98, v99
	v_cvt_pk_bf16_f32 v159, v100, v101
	v_cvt_pk_bf16_f32 v160, v90, v91
	v_cvt_pk_bf16_f32 v161, v92, v93
	global_store_dwordx4 v[162:163], v[158:161], off offset:256 sc0 sc1
	v_or_b32_e32 v162, 32, v157
	v_mad_i64_i32 v[162:163], s[30:31], v162, s55, v[146:147]
	v_cvt_pk_bf16_f32 v158, v102, v103
	v_cvt_pk_bf16_f32 v159, v104, v105
	v_cvt_pk_bf16_f32 v160, v94, v95
	v_cvt_pk_bf16_f32 v161, v96, v97
	v_lshl_add_u64 v[162:163], v[162:163], 0, v[148:149]
	global_store_dwordx4 v[162:163], v[158:161], off sc0 sc1
	s_nop 1
	v_cvt_pk_bf16_f32 v158, v82, v83
	v_cvt_pk_bf16_f32 v159, v84, v85
	v_cvt_pk_bf16_f32 v160, v74, v75
	v_cvt_pk_bf16_f32 v161, v76, v77
	global_store_dwordx4 v[162:163], v[158:161], off offset:256 sc0 sc1
	v_or_b32_e32 v162, 48, v157
	v_mad_i64_i32 v[162:163], s[30:31], v162, s55, v[146:147]
	v_cvt_pk_bf16_f32 v158, v86, v87
	v_cvt_pk_bf16_f32 v159, v88, v89
	v_cvt_pk_bf16_f32 v160, v78, v79
	v_cvt_pk_bf16_f32 v161, v80, v81
	v_lshl_add_u64 v[162:163], v[162:163], 0, v[148:149]
	global_store_dwordx4 v[162:163], v[158:161], off sc0 sc1
	s_nop 1
	v_cvt_pk_bf16_f32 v158, v70, v71
	v_cvt_pk_bf16_f32 v159, v72, v73
	v_cvt_pk_bf16_f32 v160, v66, v67
	v_cvt_pk_bf16_f32 v161, v68, v69
	global_store_dwordx4 v[162:163], v[158:161], off offset:256 sc0 sc1
	v_add_u32_e32 v162, 0x80, v157
	v_mad_i64_i32 v[162:163], s[30:31], v162, s55, v[146:147]
	v_cvt_pk_bf16_f32 v158, v62, v63
	v_cvt_pk_bf16_f32 v159, v64, v65
	v_cvt_pk_bf16_f32 v160, v58, v59
	v_cvt_pk_bf16_f32 v161, v60, v61
	v_lshl_add_u64 v[162:163], v[162:163], 0, v[148:149]
	global_store_dwordx4 v[162:163], v[158:161], off sc0 sc1
	s_nop 1
	v_cvt_pk_bf16_f32 v158, v50, v51
	v_cvt_pk_bf16_f32 v159, v52, v53
	v_cvt_pk_bf16_f32 v160, v42, v43
	v_cvt_pk_bf16_f32 v161, v44, v45
	global_store_dwordx4 v[162:163], v[158:161], off offset:256 sc0 sc1
	v_add_u32_e32 v162, 0x90, v157
	v_mad_i64_i32 v[162:163], s[30:31], v162, s55, v[146:147]
	v_cvt_pk_bf16_f32 v158, v54, v55
	v_cvt_pk_bf16_f32 v159, v56, v57
	v_cvt_pk_bf16_f32 v160, v46, v47
	v_cvt_pk_bf16_f32 v161, v48, v49
	v_lshl_add_u64 v[162:163], v[162:163], 0, v[148:149]
	global_store_dwordx4 v[162:163], v[158:161], off sc0 sc1
	s_nop 1
	v_cvt_pk_bf16_f32 v158, v34, v35
	v_cvt_pk_bf16_f32 v159, v36, v37
	v_cvt_pk_bf16_f32 v160, v26, v27
	v_cvt_pk_bf16_f32 v161, v28, v29
	global_store_dwordx4 v[162:163], v[158:161], off offset:256 sc0 sc1
	v_add_u32_e32 v162, 0xa0, v157
	v_mad_i64_i32 v[162:163], s[30:31], v162, s55, v[146:147]
	v_add_u32_e32 v157, 0xb0, v157
	v_cvt_pk_bf16_f32 v158, v38, v39
	v_cvt_pk_bf16_f32 v159, v40, v41
	v_cvt_pk_bf16_f32 v160, v30, v31
	v_cvt_pk_bf16_f32 v161, v32, v33
	v_lshl_add_u64 v[162:163], v[162:163], 0, v[148:149]
	v_mad_i64_i32 v[146:147], s[30:31], v157, s55, v[146:147]
	global_store_dwordx4 v[162:163], v[158:161], off sc0 sc1
	s_nop 1
	v_cvt_pk_bf16_f32 v158, v18, v19
	v_cvt_pk_bf16_f32 v159, v20, v21
	v_cvt_pk_bf16_f32 v160, v10, v11
	v_cvt_pk_bf16_f32 v161, v12, v13
	global_store_dwordx4 v[162:163], v[158:161], off offset:256 sc0 sc1
	v_lshl_add_u64 v[162:163], v[146:147], 0, v[148:149]
	v_cvt_pk_bf16_f32 v146, v6, v7
	v_cvt_pk_bf16_f32 v147, v8, v9
	v_cvt_pk_bf16_f32 v148, v2, v3
	v_cvt_pk_bf16_f32 v149, v4, v5
	s_nop 0
	v_cvt_pk_bf16_f32 v158, v22, v23
	v_cvt_pk_bf16_f32 v159, v24, v25
	v_cvt_pk_bf16_f32 v160, v14, v15
	v_cvt_pk_bf16_f32 v161, v16, v17
	global_store_dwordx4 v[162:163], v[158:161], off sc0 sc1
	global_store_dwordx4 v[162:163], v[146:149], off offset:256 sc0 sc1
	s_cbranch_execnz .LBB0_1591
.LBB0_1594:
	s_nop 0
	v_lshl_add_u32 v148, s68, 8, v151
	v_lshl_or_b32 v146, s67, 8, v152
	v_ashrrev_i32_e32 v149, 31, v148
	v_ashrrev_i32_e32 v147, 31, v146
	v_lshlrev_b64 v[158:159], 14, v[148:149]
	v_lshl_add_u64 v[158:159], s[10:11], 0, v[158:159]
	v_lshlrev_b64 v[160:161], 1, v[146:147]
	v_lshl_add_u64 v[146:147], v[158:159], 0, v[160:161]
	v_cvt_pk_bf16_f32 v62, v62, v63
	v_cvt_pk_bf16_f32 v63, v64, v65
	v_cvt_pk_bf16_f32 v64, v58, v59
	v_add_co_u32_e32 v58, vcc, s62, v146
	v_cvt_pk_bf16_f32 v114, v114, v115
	v_cvt_pk_bf16_f32 v115, v116, v117
	v_cvt_pk_bf16_f32 v116, v106, v107
	v_or_b32_e32 v106, 16, v148
	s_nop 0
	v_addc_co_u32_e32 v59, vcc, 0, v147, vcc
	v_ashrrev_i32_e32 v107, 31, v106
	v_cvt_pk_bf16_f32 v98, v98, v99
	v_cvt_pk_bf16_f32 v99, v100, v101
	v_cvt_pk_bf16_f32 v100, v90, v91
	v_or_b32_e32 v90, 32, v148
	v_cvt_pk_bf16_f32 v50, v50, v51
	v_cvt_pk_bf16_f32 v51, v52, v53
	v_cvt_pk_bf16_f32 v53, v44, v45
	v_cvt_pk_bf16_f32 v44, v46, v47
	v_add_co_u32_e32 v46, vcc, s63, v146
	v_lshlrev_b64 v[106:107], 14, v[106:107]
	v_ashrrev_i32_e32 v91, 31, v90
	v_cvt_pk_bf16_f32 v82, v82, v83
	v_cvt_pk_bf16_f32 v83, v84, v85
	v_cvt_pk_bf16_f32 v84, v74, v75
	v_or_b32_e32 v74, 48, v148
	v_addc_co_u32_e32 v47, vcc, 0, v147, vcc
	v_lshl_add_u64 v[106:107], s[10:11], 0, v[106:107]
	v_lshlrev_b64 v[90:91], 14, v[90:91]
	v_ashrrev_i32_e32 v75, 31, v74
	v_cvt_pk_bf16_f32 v70, v70, v71
	v_cvt_pk_bf16_f32 v71, v72, v73
	v_cvt_pk_bf16_f32 v72, v66, v67
	v_lshl_add_u64 v[66:67], v[146:147], 0, s[16:17]
	v_cvt_pk_bf16_f32 v34, v34, v35
	v_cvt_pk_bf16_f32 v35, v36, v37
	v_cvt_pk_bf16_f32 v37, v28, v29
	v_cvt_pk_bf16_f32 v28, v30, v31
	v_add_co_u32_e32 v30, vcc, s64, v146
	v_cvt_pk_bf16_f32 v117, v108, v109
	global_store_dwordx4 v[146:147], v[114:117], off offset:256 sc0 sc1
	v_lshl_add_u64 v[90:91], s[10:11], 0, v[90:91]
	v_lshlrev_b64 v[74:75], 14, v[74:75]
	v_lshl_add_u64 v[114:115], v[106:107], 0, v[160:161]
	v_cvt_pk_bf16_f32 v52, v42, v43
	global_store_dwordx4 v[66:67], v[50:53], off offset:256 sc0 sc1
	v_addc_co_u32_e32 v31, vcc, 0, v147, vcc
	s_nop 0
	v_lshl_add_u64 v[50:51], v[146:147], 0, s[18:19]
	v_cvt_pk_bf16_f32 v101, v92, v93
	global_store_dwordx4 v[114:115], v[98:101], off offset:256 sc0 sc1
	v_lshl_add_u64 v[74:75], s[10:11], 0, v[74:75]
	v_cvt_pk_bf16_f32 v36, v26, v27
	global_store_dwordx4 v[50:51], v[34:37], off offset:256 sc0 sc1
	v_lshl_add_u64 v[98:99], v[90:91], 0, v[160:161]
	v_cvt_pk_bf16_f32 v18, v18, v19
	v_cvt_pk_bf16_f32 v19, v20, v21
	v_cvt_pk_bf16_f32 v21, v12, v13
	v_cvt_pk_bf16_f32 v12, v14, v15
	s_nop 0
	v_lshl_add_u64 v[34:35], v[146:147], 0, s[20:21]
	v_add_co_u32_e32 v14, vcc, s65, v146
	v_cvt_pk_bf16_f32 v85, v76, v77
	global_store_dwordx4 v[98:99], v[82:85], off offset:256 sc0 sc1
	v_cvt_pk_bf16_f32 v20, v10, v11
	global_store_dwordx4 v[34:35], v[18:21], off offset:256 sc0 sc1
	v_addc_co_u32_e32 v15, vcc, 0, v147, vcc
	v_lshl_add_u64 v[82:83], v[74:75], 0, v[160:161]
	v_lshl_add_u64 v[18:19], v[146:147], 0, s[22:23]
	v_cvt_pk_bf16_f32 v126, v126, v127
	v_cvt_pk_bf16_f32 v127, v128, v129
	v_cvt_pk_bf16_f32 v128, v122, v123
	v_cvt_pk_bf16_f32 v129, v124, v125
	global_store_dwordx4 v[146:147], v[126:129], off sc0 sc1
	v_cvt_pk_bf16_f32 v106, v118, v119
	v_cvt_pk_bf16_f32 v107, v120, v121
	v_cvt_pk_bf16_f32 v108, v110, v111
	v_cvt_pk_bf16_f32 v109, v112, v113
	global_store_dwordx4 v[114:115], v[106:109], off sc0 sc1
	v_cvt_pk_bf16_f32 v90, v102, v103
	v_cvt_pk_bf16_f32 v91, v104, v105
	v_cvt_pk_bf16_f32 v92, v94, v95
	v_cvt_pk_bf16_f32 v93, v96, v97
	global_store_dwordx4 v[98:99], v[90:93], off sc0 sc1
	v_cvt_pk_bf16_f32 v74, v86, v87
	v_cvt_pk_bf16_f32 v75, v88, v89
	v_cvt_pk_bf16_f32 v76, v78, v79
	v_cvt_pk_bf16_f32 v77, v80, v81
	global_store_dwordx4 v[82:83], v[74:77], off sc0 sc1
	v_cvt_pk_bf16_f32 v73, v68, v69
	global_store_dwordx4 v[82:83], v[70:73], off offset:256 sc0 sc1
	v_cvt_pk_bf16_f32 v65, v60, v61
	global_store_dwordx4 v[58:59], v[62:65], off sc0 sc1
	v_cvt_pk_bf16_f32 v42, v54, v55
	v_cvt_pk_bf16_f32 v43, v56, v57
	v_cvt_pk_bf16_f32 v45, v48, v49
	global_store_dwordx4 v[46:47], v[42:45], off sc0 sc1
	v_cvt_pk_bf16_f32 v26, v38, v39
	v_cvt_pk_bf16_f32 v27, v40, v41
	v_cvt_pk_bf16_f32 v29, v32, v33
	global_store_dwordx4 v[30:31], v[26:29], off sc0 sc1
	v_cvt_pk_bf16_f32 v10, v22, v23
	v_cvt_pk_bf16_f32 v11, v24, v25
	v_cvt_pk_bf16_f32 v13, v16, v17
	global_store_dwordx4 v[14:15], v[10:13], off sc0 sc1
	v_cvt_pk_bf16_f32 v6, v6, v7
	v_cvt_pk_bf16_f32 v7, v8, v9
	v_cvt_pk_bf16_f32 v8, v2, v3
	v_cvt_pk_bf16_f32 v9, v4, v5
	global_store_dwordx4 v[18:19], v[6:9], off offset:256 sc0 sc1
	s_and_b64 vcc, exec, s[4:5]
	s_mov_b64 s[4:5], -1
	s_cbranch_vccnz .LBB0_1573
